# MLP1 epilogues: first shift@W vector pair requested together with the sum-of-squares loads
# speedup vs baseline: 1.0444x; 1.0024x over previous
.LBB0_130:
	s_add_u32 s8, s60, 0xfffc0080
	s_addc_u32 s9, s61, -1
	s_add_i32 s16, 0, 0x10000
	v_add_u32_e32 v150, s16, v168
	ds_read_b128 v[128:131], v150
	ds_read_b128 v[132:135], v150 offset:1024
	ds_read_b128 v[146:149], v150 offset:2048
	ds_read_b128 v[150:153], v150 offset:3072
	s_cmp_eq_u32 s15, 12
	s_cselect_b32 s9, s5, s9
	s_cselect_b32 s8, s10, s8
	s_cselect_b32 s63, s1, s14
	s_cselect_b32 s62, s12, s13
	v_lshl_add_u64 v[164:165], s[60:61], 0, v[142:143]
	s_add_i32 m0, s38, 0xc000
	ds_read_b128 v[154:157], v170
	ds_read_b128 v[172:175], v170 offset:1024
	ds_read_b128 v[176:179], v170 offset:2048
	ds_read_b128 v[180:183], v170 offset:3072
	ds_read_b128 v[184:187], v170 offset:4096
	ds_read_b128 v[188:191], v170 offset:5120
	ds_read_b128 v[192:195], v170 offset:6144
	ds_read_b128 v[196:199], v170 offset:7168
	global_load_lds_dwordx4 v[164:165], off
	v_lshl_add_u64 v[164:165], s[60:61], 0, v[144:145]
	s_add_i32 m0, s38, 0xe000
	s_nop 0
	global_load_lds_dwordx4 v[164:165], off
	s_waitcnt lgkmcnt(8)
	s_barrier
	s_waitcnt lgkmcnt(0)
	s_setprio 1
	s_waitcnt lgkmcnt(0)
	v_mfma_f32_16x16x32_bf16 v[124:127], v[128:131], v[154:157], v[124:127]
	v_mfma_f32_16x16x32_bf16 v[120:123], v[146:149], v[154:157], v[120:123]
	v_mfma_f32_16x16x32_bf16 v[116:119], v[128:131], v[176:179], v[116:119]
	v_mfma_f32_16x16x32_bf16 v[112:115], v[146:149], v[176:179], v[112:115]
	v_mfma_f32_16x16x32_bf16 v[108:111], v[128:131], v[184:187], v[108:111]
	v_mfma_f32_16x16x32_bf16 v[104:107], v[146:149], v[184:187], v[104:107]
	v_mfma_f32_16x16x32_bf16 v[100:103], v[128:131], v[192:195], v[100:103]
	v_mfma_f32_16x16x32_bf16 v[96:99], v[146:149], v[192:195], v[96:99]
	v_mfma_f32_16x16x32_bf16 v[124:127], v[132:135], v[172:175], v[124:127]
	v_mfma_f32_16x16x32_bf16 v[120:123], v[150:153], v[172:175], v[120:123]
	v_mfma_f32_16x16x32_bf16 v[116:119], v[132:135], v[180:183], v[116:119]
	v_mfma_f32_16x16x32_bf16 v[112:115], v[150:153], v[180:183], v[112:115]
	v_mfma_f32_16x16x32_bf16 v[108:111], v[132:135], v[188:191], v[108:111]
	v_mfma_f32_16x16x32_bf16 v[104:107], v[150:153], v[188:191], v[104:107]
	v_mfma_f32_16x16x32_bf16 v[100:103], v[132:135], v[196:199], v[100:103]
	v_mfma_f32_16x16x32_bf16 v[96:99], v[150:153], v[196:199], v[96:99]
	s_setprio 0
	s_barrier
	s_add_i32 s18, 0, 0x14000
	s_add_i32 s16, s16, s37
	v_add_u32_e32 v158, s18, v168
	v_lshl_add_u64 v[164:165], s[62:63], 0, v[160:161]
	s_mov_b32 m0, s16
	ds_read_b128 v[200:203], v158
	ds_read_b128 v[204:207], v158 offset:1024
	ds_read_b128 v[208:211], v158 offset:2048
	ds_read_b128 v[212:215], v158 offset:3072
	global_load_lds_dwordx4 v[164:165], off
	v_lshl_add_u64 v[166:167], s[62:63], 0, v[136:137]
	s_add_i32 m0, s16, 0x2000
	s_nop 0
	global_load_lds_dwordx4 v[166:167], off
	s_barrier
	s_waitcnt lgkmcnt(0)
	s_setprio 1
	s_waitcnt lgkmcnt(0)
	v_mfma_f32_16x16x32_bf16 v[68:71], v[200:203], v[154:157], v[68:71]
	v_mfma_f32_16x16x32_bf16 v[64:67], v[208:211], v[154:157], v[64:67]
	v_mfma_f32_16x16x32_bf16 v[52:55], v[200:203], v[176:179], v[52:55]
	v_mfma_f32_16x16x32_bf16 v[48:51], v[208:211], v[176:179], v[48:51]
	v_mfma_f32_16x16x32_bf16 v[44:47], v[200:203], v[184:187], v[44:47]
	v_mfma_f32_16x16x32_bf16 v[40:43], v[208:211], v[184:187], v[40:43]
	v_mfma_f32_16x16x32_bf16 v[36:39], v[200:203], v[192:195], v[36:39]
	v_mfma_f32_16x16x32_bf16 v[32:35], v[208:211], v[192:195], v[32:35]
	v_mfma_f32_16x16x32_bf16 v[68:71], v[204:207], v[172:175], v[68:71]
	v_mfma_f32_16x16x32_bf16 v[64:67], v[212:215], v[172:175], v[64:67]
	v_mfma_f32_16x16x32_bf16 v[52:55], v[204:207], v[180:183], v[52:55]
	v_mfma_f32_16x16x32_bf16 v[48:51], v[212:215], v[180:183], v[48:51]
	v_mfma_f32_16x16x32_bf16 v[44:47], v[204:207], v[188:191], v[44:47]
	v_mfma_f32_16x16x32_bf16 v[40:43], v[212:215], v[188:191], v[40:43]
	v_mfma_f32_16x16x32_bf16 v[36:39], v[204:207], v[196:199], v[36:39]
	v_mfma_f32_16x16x32_bf16 v[32:35], v[212:215], v[196:199], v[32:35]
	s_setprio 0
	s_mov_b32 m0, s38
	v_lshl_add_u64 v[216:217], s[8:9], 0, v[140:141]
	s_barrier
	ds_read_b128 v[154:157], v170 offset:16384
	ds_read_b128 v[172:175], v170 offset:17408
	ds_read_b128 v[176:179], v170 offset:18432
	ds_read_b128 v[180:183], v170 offset:19456
	ds_read_b128 v[184:187], v170 offset:20480
	ds_read_b128 v[188:191], v170 offset:21504
	ds_read_b128 v[192:195], v170 offset:22528
	ds_read_b128 v[196:199], v170 offset:23552
	global_load_lds_dwordx4 v[216:217], off
	v_lshl_add_u64 v[218:219], s[8:9], 0, v[138:139]
	s_mov_b32 m0, s39
	s_nop 0
	global_load_lds_dwordx4 v[218:219], off
	s_barrier
	s_waitcnt lgkmcnt(0)
	s_setprio 1
	s_waitcnt lgkmcnt(0)
	v_mfma_f32_16x16x32_bf16 v[92:95], v[128:131], v[154:157], v[92:95]
	v_mfma_f32_16x16x32_bf16 v[88:91], v[146:149], v[154:157], v[88:91]
	v_mfma_f32_16x16x32_bf16 v[84:87], v[128:131], v[176:179], v[84:87]
	v_mfma_f32_16x16x32_bf16 v[80:83], v[146:149], v[176:179], v[80:83]
	v_mfma_f32_16x16x32_bf16 v[76:79], v[128:131], v[184:187], v[76:79]
	v_mfma_f32_16x16x32_bf16 v[72:75], v[146:149], v[184:187], v[72:75]
	v_mfma_f32_16x16x32_bf16 v[60:63], v[128:131], v[192:195], v[60:63]
	v_mfma_f32_16x16x32_bf16 v[56:59], v[146:149], v[192:195], v[56:59]
	v_mfma_f32_16x16x32_bf16 v[92:95], v[132:135], v[172:175], v[92:95]
	v_mfma_f32_16x16x32_bf16 v[88:91], v[150:153], v[172:175], v[88:91]
	v_mfma_f32_16x16x32_bf16 v[84:87], v[132:135], v[180:183], v[84:87]
	v_mfma_f32_16x16x32_bf16 v[80:83], v[150:153], v[180:183], v[80:83]
	v_mfma_f32_16x16x32_bf16 v[76:79], v[132:135], v[188:191], v[76:79]
	v_mfma_f32_16x16x32_bf16 v[72:75], v[150:153], v[188:191], v[72:75]
	v_mfma_f32_16x16x32_bf16 v[60:63], v[132:135], v[196:199], v[60:63]
	v_mfma_f32_16x16x32_bf16 v[56:59], v[150:153], v[196:199], v[56:59]
	s_setprio 0
	s_barrier
	s_add_u32 s16, s62, 0x40000
	s_addc_u32 s17, s63, 0
	s_add_i32 s18, s18, s37
	v_lshl_add_u64 v[128:129], s[16:17], 0, v[160:161]
	s_mov_b32 m0, s18
	s_nop 0
	global_load_lds_dwordx4 v[128:129], off
	v_lshl_add_u64 v[128:129], s[16:17], 0, v[136:137]
	s_add_i32 m0, s18, 0x2000
	s_nop 0
	global_load_lds_dwordx4 v[128:129], off
	s_waitcnt vmcnt(6)
	s_barrier
	s_setprio 1
	v_mfma_f32_16x16x32_bf16 v[28:31], v[200:203], v[154:157], v[28:31]
	v_mfma_f32_16x16x32_bf16 v[24:27], v[208:211], v[154:157], v[24:27]
	v_mfma_f32_16x16x32_bf16 v[20:23], v[200:203], v[176:179], v[20:23]
	v_mfma_f32_16x16x32_bf16 v[16:19], v[208:211], v[176:179], v[16:19]
	v_mfma_f32_16x16x32_bf16 v[12:15], v[200:203], v[184:187], v[12:15]
	v_mfma_f32_16x16x32_bf16 v[8:11], v[208:211], v[184:187], v[8:11]
	v_mfma_f32_16x16x32_bf16 v[4:7], v[200:203], v[192:195], v[4:7]
	v_mfma_f32_16x16x32_bf16 v[0:3], v[208:211], v[192:195], v[0:3]
	v_mfma_f32_16x16x32_bf16 v[28:31], v[204:207], v[172:175], v[28:31]
	v_mfma_f32_16x16x32_bf16 v[24:27], v[212:215], v[172:175], v[24:27]
	v_mfma_f32_16x16x32_bf16 v[20:23], v[204:207], v[180:183], v[20:23]
	v_mfma_f32_16x16x32_bf16 v[16:19], v[212:215], v[180:183], v[16:19]
	v_mfma_f32_16x16x32_bf16 v[12:15], v[204:207], v[188:191], v[12:15]
	v_mfma_f32_16x16x32_bf16 v[8:11], v[212:215], v[188:191], v[8:11]
	v_mfma_f32_16x16x32_bf16 v[4:7], v[204:207], v[196:199], v[4:7]
	v_mfma_f32_16x16x32_bf16 v[0:3], v[212:215], v[196:199], v[0:3]
	s_setprio 0
	s_add_i32 s16, 0, 0x18000
	v_add_u32_e32 v150, s16, v168
	s_barrier
	ds_read_b128 v[128:131], v150
	ds_read_b128 v[132:135], v150 offset:1024
	ds_read_b128 v[146:149], v150 offset:2048
	ds_read_b128 v[150:153], v150 offset:3072
	s_add_u32 s8, s8, 0x40000
	s_addc_u32 s9, s9, 0
	s_mov_b32 m0, s40
	v_lshl_add_u64 v[200:201], s[8:9], 0, v[140:141]
	ds_read_b128 v[154:157], v170 offset:32768
	ds_read_b128 v[172:175], v170 offset:33792
	ds_read_b128 v[176:179], v170 offset:34816
	ds_read_b128 v[180:183], v170 offset:35840
	ds_read_b128 v[184:187], v170 offset:36864
	ds_read_b128 v[188:191], v170 offset:37888
	ds_read_b128 v[192:195], v170 offset:38912
	ds_read_b128 v[196:199], v170 offset:39936
	global_load_lds_dwordx4 v[200:201], off
	v_lshl_add_u64 v[200:201], s[8:9], 0, v[138:139]
	s_mov_b32 m0, s41
	s_nop 0
	global_load_lds_dwordx4 v[200:201], off
	s_waitcnt lgkmcnt(8)
	s_barrier
	s_waitcnt lgkmcnt(0)
	s_setprio 1
	s_waitcnt lgkmcnt(0)
	v_mfma_f32_16x16x32_bf16 v[124:127], v[128:131], v[154:157], v[124:127]
	v_mfma_f32_16x16x32_bf16 v[120:123], v[146:149], v[154:157], v[120:123]
	v_mfma_f32_16x16x32_bf16 v[116:119], v[128:131], v[176:179], v[116:119]
	v_mfma_f32_16x16x32_bf16 v[112:115], v[146:149], v[176:179], v[112:115]
	v_mfma_f32_16x16x32_bf16 v[108:111], v[128:131], v[184:187], v[108:111]
	v_mfma_f32_16x16x32_bf16 v[104:107], v[146:149], v[184:187], v[104:107]
	v_mfma_f32_16x16x32_bf16 v[100:103], v[128:131], v[192:195], v[100:103]
	v_mfma_f32_16x16x32_bf16 v[96:99], v[146:149], v[192:195], v[96:99]
	v_mfma_f32_16x16x32_bf16 v[124:127], v[132:135], v[172:175], v[124:127]
	v_mfma_f32_16x16x32_bf16 v[120:123], v[150:153], v[172:175], v[120:123]
	v_mfma_f32_16x16x32_bf16 v[116:119], v[132:135], v[180:183], v[116:119]
	v_mfma_f32_16x16x32_bf16 v[112:115], v[150:153], v[180:183], v[112:115]
	v_mfma_f32_16x16x32_bf16 v[108:111], v[132:135], v[188:191], v[108:111]
	v_mfma_f32_16x16x32_bf16 v[104:107], v[150:153], v[188:191], v[104:107]
	v_mfma_f32_16x16x32_bf16 v[100:103], v[132:135], v[196:199], v[100:103]
	v_mfma_f32_16x16x32_bf16 v[96:99], v[150:153], v[196:199], v[96:99]
	s_setprio 0
	s_barrier
	s_add_i32 s17, 0, 0x1c000
	s_add_i32 s8, s16, s37
	v_add_u32_e32 v158, s17, v168
	v_lshl_add_u64 v[164:165], v[164:165], 0, s[74:75]
	s_mov_b32 m0, s8
	ds_read_b128 v[200:203], v158
	ds_read_b128 v[204:207], v158 offset:1024
	ds_read_b128 v[208:211], v158 offset:2048
	ds_read_b128 v[212:215], v158 offset:3072
	global_load_lds_dwordx4 v[164:165], off
	v_lshl_add_u64 v[164:165], v[166:167], 0, s[74:75]
	s_add_i32 m0, s8, 0x2000
	s_nop 0
	global_load_lds_dwordx4 v[164:165], off
	s_barrier
	s_waitcnt lgkmcnt(0)
	s_setprio 1
	s_waitcnt lgkmcnt(0)
	v_mfma_f32_16x16x32_bf16 v[68:71], v[200:203], v[154:157], v[68:71]
	v_mfma_f32_16x16x32_bf16 v[64:67], v[208:211], v[154:157], v[64:67]
	v_mfma_f32_16x16x32_bf16 v[52:55], v[200:203], v[176:179], v[52:55]
	v_mfma_f32_16x16x32_bf16 v[48:51], v[208:211], v[176:179], v[48:51]
	v_mfma_f32_16x16x32_bf16 v[44:47], v[200:203], v[184:187], v[44:47]
	v_mfma_f32_16x16x32_bf16 v[40:43], v[208:211], v[184:187], v[40:43]
	v_mfma_f32_16x16x32_bf16 v[36:39], v[200:203], v[192:195], v[36:39]
	v_mfma_f32_16x16x32_bf16 v[32:35], v[208:211], v[192:195], v[32:35]
	v_mfma_f32_16x16x32_bf16 v[68:71], v[204:207], v[172:175], v[68:71]
	v_mfma_f32_16x16x32_bf16 v[64:67], v[212:215], v[172:175], v[64:67]
	v_mfma_f32_16x16x32_bf16 v[52:55], v[204:207], v[180:183], v[52:55]
	v_mfma_f32_16x16x32_bf16 v[48:51], v[212:215], v[180:183], v[48:51]
	v_mfma_f32_16x16x32_bf16 v[44:47], v[204:207], v[188:191], v[44:47]
	v_mfma_f32_16x16x32_bf16 v[40:43], v[212:215], v[188:191], v[40:43]
	v_mfma_f32_16x16x32_bf16 v[36:39], v[204:207], v[196:199], v[36:39]
	v_mfma_f32_16x16x32_bf16 v[32:35], v[212:215], v[196:199], v[32:35]
	s_setprio 0
	s_mov_b32 m0, s42
	v_lshl_add_u64 v[164:165], v[216:217], 0, s[74:75]
	s_barrier
	ds_read_b128 v[154:157], v170 offset:49152
	ds_read_b128 v[172:175], v170 offset:50176
	ds_read_b128 v[176:179], v170 offset:51200
	ds_read_b128 v[180:183], v170 offset:52224
	ds_read_b128 v[184:187], v170 offset:53248
	ds_read_b128 v[188:191], v170 offset:54272
	ds_read_b128 v[192:195], v170 offset:55296
	ds_read_b128 v[196:199], v170 offset:56320
	global_load_lds_dwordx4 v[164:165], off
	v_lshl_add_u64 v[164:165], v[218:219], 0, s[74:75]
	s_mov_b32 m0, s43
	s_nop 0
	global_load_lds_dwordx4 v[164:165], off
	s_barrier
	s_waitcnt lgkmcnt(0)
	s_setprio 1
	s_waitcnt lgkmcnt(0)
	v_mfma_f32_16x16x32_bf16 v[92:95], v[128:131], v[154:157], v[92:95]
	v_mfma_f32_16x16x32_bf16 v[88:91], v[146:149], v[154:157], v[88:91]
	v_mfma_f32_16x16x32_bf16 v[84:87], v[128:131], v[176:179], v[84:87]
	v_mfma_f32_16x16x32_bf16 v[80:83], v[146:149], v[176:179], v[80:83]
	v_mfma_f32_16x16x32_bf16 v[76:79], v[128:131], v[184:187], v[76:79]
	v_mfma_f32_16x16x32_bf16 v[72:75], v[146:149], v[184:187], v[72:75]
	v_mfma_f32_16x16x32_bf16 v[60:63], v[128:131], v[192:195], v[60:63]
	v_mfma_f32_16x16x32_bf16 v[56:59], v[146:149], v[192:195], v[56:59]
	v_mfma_f32_16x16x32_bf16 v[92:95], v[132:135], v[172:175], v[92:95]
	v_mfma_f32_16x16x32_bf16 v[88:91], v[150:153], v[172:175], v[88:91]
	v_mfma_f32_16x16x32_bf16 v[84:87], v[132:135], v[180:183], v[84:87]
	v_mfma_f32_16x16x32_bf16 v[80:83], v[150:153], v[180:183], v[80:83]
	v_mfma_f32_16x16x32_bf16 v[76:79], v[132:135], v[188:191], v[76:79]
	v_mfma_f32_16x16x32_bf16 v[72:75], v[150:153], v[188:191], v[72:75]
	v_mfma_f32_16x16x32_bf16 v[60:63], v[132:135], v[196:199], v[60:63]
	v_mfma_f32_16x16x32_bf16 v[56:59], v[150:153], v[196:199], v[56:59]
	s_setprio 0
	s_barrier
	s_add_u32 s8, s62, 0x40080
	s_addc_u32 s9, s63, 0
	s_add_i32 s16, s17, s37
	v_lshl_add_u64 v[128:129], s[8:9], 0, v[160:161]
	s_mov_b32 m0, s16
	s_nop 0
	global_load_lds_dwordx4 v[128:129], off
	v_lshl_add_u64 v[128:129], s[8:9], 0, v[136:137]
	s_add_i32 m0, s16, 0x2000
	s_nop 0
	global_load_lds_dwordx4 v[128:129], off
	s_waitcnt vmcnt(6)
	s_barrier
	s_setprio 1
	v_mfma_f32_16x16x32_bf16 v[28:31], v[200:203], v[154:157], v[28:31]
	v_mfma_f32_16x16x32_bf16 v[24:27], v[208:211], v[154:157], v[24:27]
	v_mfma_f32_16x16x32_bf16 v[20:23], v[200:203], v[176:179], v[20:23]
	v_mfma_f32_16x16x32_bf16 v[16:19], v[208:211], v[176:179], v[16:19]
	v_mfma_f32_16x16x32_bf16 v[12:15], v[200:203], v[184:187], v[12:15]
	v_mfma_f32_16x16x32_bf16 v[8:11], v[208:211], v[184:187], v[8:11]
	v_mfma_f32_16x16x32_bf16 v[4:7], v[200:203], v[192:195], v[4:7]
	v_mfma_f32_16x16x32_bf16 v[0:3], v[208:211], v[192:195], v[0:3]
	v_mfma_f32_16x16x32_bf16 v[28:31], v[204:207], v[172:175], v[28:31]
	v_mfma_f32_16x16x32_bf16 v[24:27], v[212:215], v[172:175], v[24:27]
	v_mfma_f32_16x16x32_bf16 v[20:23], v[204:207], v[180:183], v[20:23]
	v_mfma_f32_16x16x32_bf16 v[16:19], v[212:215], v[180:183], v[16:19]
	v_mfma_f32_16x16x32_bf16 v[12:15], v[204:207], v[188:191], v[12:15]
	v_mfma_f32_16x16x32_bf16 v[8:11], v[212:215], v[188:191], v[8:11]
	v_mfma_f32_16x16x32_bf16 v[4:7], v[204:207], v[196:199], v[4:7]
	v_mfma_f32_16x16x32_bf16 v[0:3], v[212:215], v[196:199], v[0:3]
	s_setprio 0
	s_add_i32 s15, s15, 2
	s_add_u32 s60, s60, 0x100
	s_addc_u32 s61, s61, 0
	s_add_u32 s13, s13, 0x100
	s_addc_u32 s14, s14, 0
	s_cmp_gt_u32 s15, 13
	s_barrier
	s_cbranch_scc0 .LBB0_130
	v_lshl_add_u32 v146, s65, 8, v159
	v_readlane_b32 s8, v250, 14
	v_ashrrev_i32_e32 v147, 31, v146
	v_readlane_b32 s9, v250, 15
	v_readlane_b32 s1, v250, 16
	v_lshl_or_b32 v156, s66, 8, v169
	v_lshl_add_u64 v[128:129], v[146:147], 3, s[8:9]
	global_load_dwordx2 v[130:131], v[128:129], off
	global_load_dwordx2 v[218:219], v[128:129], off offset:128
	global_load_dwordx2 v[220:221], v[128:129], off offset:256
	global_load_dwordx2 v[222:223], v[128:129], off offset:384
	global_load_dwordx2 v[224:225], v[128:129], off offset:1024
	global_load_dwordx2 v[226:227], v[128:129], off offset:1152
	global_load_dwordx2 v[228:229], v[128:129], off offset:1280
	global_load_dwordx2 v[230:231], v[128:129], off offset:1408
	s_ashr_i32 s8, s65, 5
	s_ashr_i32 s9, s8, 31
	s_lshl_b64 s[8:9], s[8:9], 14
	s_add_u32 s8, s1, s8
	v_readlane_b32 s1, v250, 17
	v_ashrrev_i32_e32 v157, 31, v156
	s_addc_u32 s9, s1, s9
	v_lshl_add_u64 v[164:165], v[156:157], 2, s[8:9]
	global_load_dwordx4 v[232:235], v[164:165], off offset:16
	global_load_dwordx4 v[236:239], v[164:165], off
	v_readlane_b32 s8, v253, 29
	v_readlane_b32 s9, v253, 30
	s_mov_b32 s1, 0x100000
	s_mov_b32 s66, s0
	s_mov_b32 s65, s4
	s_mov_b64 s[20:21], s[6:7]
	v_readlane_b32 s62, v255, 4
	v_readlane_b32 s63, v255, 5
	s_waitcnt vmcnt(0)
	v_ffbh_u32_e32 v132, v131
	v_min_u32_e32 v132, 32, v132
	v_lshlrev_b64 v[130:131], v132, v[130:131]
	v_min_u32_e32 v130, 1, v130
	v_or_b32_e32 v130, v131, v130
	v_cvt_f32_u32_e32 v130, v130
	v_sub_u32_e32 v131, 32, v132
	v_ldexp_f32 v130, v130, v131
	v_mul_f32_e32 v130, 0x37800000, v130
	v_fmamk_f32 v158, v130, 0x3a800000, v240
	v_mov_b32_e32 v130, v218
	v_mov_b32_e32 v131, v219
	v_cmp_gt_f32_e32 vcc, s53, v158
	v_mul_f32_e32 v162, 0x4b800000, v158
	v_ffbh_u32_e32 v132, v131
	v_min_u32_e32 v132, 32, v132
	v_lshlrev_b64 v[130:131], v132, v[130:131]
	v_min_u32_e32 v130, 1, v130
	v_or_b32_e32 v130, v131, v130
	v_cvt_f32_u32_e32 v130, v130
	v_sub_u32_e32 v131, 32, v132
	v_cndmask_b32_e32 v158, v158, v162, vcc
	v_rsq_f32_e32 v158, v158
	v_ldexp_f32 v130, v130, v131
	v_mul_f32_e32 v130, 0x37800000, v130
	v_fmamk_f32 v171, v130, 0x3a800000, v240
	v_mov_b32_e32 v130, v220
	v_mov_b32_e32 v131, v221
	v_mul_f32_e32 v162, 0x45800000, v158
	v_cndmask_b32_e32 v184, v158, v162, vcc
	v_cmp_gt_f32_e32 vcc, s53, v171
	v_mul_f32_e32 v158, 0x4b800000, v171
	v_ffbh_u32_e32 v132, v131
	v_min_u32_e32 v132, 32, v132
	v_lshlrev_b64 v[130:131], v132, v[130:131]
	v_min_u32_e32 v130, 1, v130
	v_or_b32_e32 v130, v131, v130
	v_cvt_f32_u32_e32 v130, v130
	v_sub_u32_e32 v131, 32, v132
	v_cndmask_b32_e32 v158, v171, v158, vcc
	v_rsq_f32_e32 v158, v158
	v_ldexp_f32 v130, v130, v131
	v_mul_f32_e32 v130, 0x37800000, v130
	v_fmamk_f32 v172, v130, 0x3a800000, v240
	v_mov_b32_e32 v130, v222
	v_mov_b32_e32 v131, v223
	v_mul_f32_e32 v162, 0x45800000, v158
	v_cndmask_b32_e32 v182, v158, v162, vcc
	v_cmp_gt_f32_e32 vcc, s53, v172
	v_mul_f32_e32 v158, 0x4b800000, v172
	v_ffbh_u32_e32 v132, v131
	v_min_u32_e32 v132, 32, v132
	v_lshlrev_b64 v[130:131], v132, v[130:131]
	v_min_u32_e32 v130, 1, v130
	v_or_b32_e32 v130, v131, v130
	v_cvt_f32_u32_e32 v130, v130
	v_sub_u32_e32 v131, 32, v132
	v_cndmask_b32_e32 v158, v172, v158, vcc
	v_rsq_f32_e32 v158, v158
	v_ldexp_f32 v130, v130, v131
	v_mul_f32_e32 v130, 0x37800000, v130
	v_fmamk_f32 v173, v130, 0x3a800000, v240
	v_mov_b32_e32 v130, v224
	v_mov_b32_e32 v131, v225
	v_mul_f32_e32 v162, 0x45800000, v158
	v_cndmask_b32_e32 v180, v158, v162, vcc
	v_cmp_gt_f32_e32 vcc, s53, v173
	v_mul_f32_e32 v158, 0x4b800000, v173
	v_ffbh_u32_e32 v132, v131
	v_min_u32_e32 v132, 32, v132
	v_lshlrev_b64 v[130:131], v132, v[130:131]
	v_min_u32_e32 v130, 1, v130
	v_or_b32_e32 v130, v131, v130
	v_cvt_f32_u32_e32 v130, v130
	v_sub_u32_e32 v131, 32, v132
	v_cndmask_b32_e32 v158, v173, v158, vcc
	v_rsq_f32_e32 v158, v158
	v_ldexp_f32 v130, v130, v131
	v_mul_f32_e32 v130, 0x37800000, v130
	v_fmamk_f32 v174, v130, 0x3a800000, v240
	v_mov_b32_e32 v130, v226
	v_mov_b32_e32 v131, v227
	v_mul_f32_e32 v162, 0x45800000, v158
	v_cndmask_b32_e32 v178, v158, v162, vcc
	v_cmp_gt_f32_e32 vcc, s53, v174
	v_mul_f32_e32 v158, 0x4b800000, v174
	v_ffbh_u32_e32 v132, v131
	v_min_u32_e32 v132, 32, v132
	v_lshlrev_b64 v[130:131], v132, v[130:131]
	v_min_u32_e32 v130, 1, v130
	v_or_b32_e32 v130, v131, v130
	v_cvt_f32_u32_e32 v130, v130
	v_sub_u32_e32 v131, 32, v132
	v_cndmask_b32_e32 v158, v174, v158, vcc
	v_rsq_f32_e32 v158, v158
	v_ldexp_f32 v130, v130, v131
	v_mul_f32_e32 v130, 0x37800000, v130
	v_fmamk_f32 v175, v130, 0x3a800000, v240
	v_mov_b32_e32 v130, v228
	v_mov_b32_e32 v131, v229
	v_mul_f32_e32 v162, 0x45800000, v158
	v_mov_b32_e32 v128, v230
	v_mov_b32_e32 v129, v231
	v_cndmask_b32_e32 v176, v158, v162, vcc
	v_cmp_gt_f32_e32 vcc, s53, v175
	v_mul_f32_e32 v158, 0x4b800000, v175
	v_ffbh_u32_e32 v132, v131
	v_min_u32_e32 v132, 32, v132
	v_lshlrev_b64 v[130:131], v132, v[130:131]
	v_min_u32_e32 v130, 1, v130
	v_or_b32_e32 v130, v131, v130
	v_cvt_f32_u32_e32 v130, v130
	v_sub_u32_e32 v131, 32, v132
	v_cndmask_b32_e32 v158, v175, v158, vcc
	v_rsq_f32_e32 v158, v158
	v_ldexp_f32 v130, v130, v131
	v_mul_f32_e32 v130, 0x37800000, v130
	v_fmamk_f32 v177, v130, 0x3a800000, v240
	v_ffbh_u32_e32 v130, v129
	v_min_u32_e32 v130, 32, v130
	v_lshlrev_b64 v[128:129], v130, v[128:129]
	v_min_u32_e32 v128, 1, v128
	v_or_b32_e32 v128, v129, v128
	v_cvt_f32_u32_e32 v128, v128
	v_sub_u32_e32 v129, 32, v130
	v_mul_f32_e32 v162, 0x45800000, v158
	v_cndmask_b32_e32 v174, v158, v162, vcc
	v_ldexp_f32 v128, v128, v129
	v_mul_f32_e32 v128, 0x37800000, v128
	v_fmamk_f32 v179, v128, 0x3a800000, v240
	v_mov_b32_e32 v128, v232
	v_mov_b32_e32 v129, v233
	v_mov_b32_e32 v130, v234
	v_mov_b32_e32 v131, v235
	v_mov_b32_e32 v132, v236
	v_mov_b32_e32 v133, v237
	v_mov_b32_e32 v134, v238
	v_mov_b32_e32 v135, v239
	v_cmp_gt_f32_e32 vcc, s53, v177
	v_mul_f32_e32 v158, 0x4b800000, v177
	s_waitcnt vmcnt(0)
	v_pk_add_f32 v[148:149], v[130:131], 0 op_sel_hi:[1,0]
	v_pk_add_f32 v[152:153], v[134:135], 0 op_sel_hi:[1,0]
	v_pk_add_f32 v[154:155], v[132:133], 0 op_sel_hi:[1,0]
	v_pk_add_f32 v[150:151], v[128:129], 0 op_sel_hi:[1,0]
	global_load_dwordx4 v[128:131], v[164:165], off offset:528
	global_load_dwordx4 v[132:135], v[164:165], off offset:512
	v_cndmask_b32_e32 v158, v177, v158, vcc
	v_rsq_f32_e32 v158, v158
	v_pk_fma_f32 v[122:123], v[122:123], v[184:185], v[148:149] op_sel_hi:[1,0,1]
	v_pk_fma_f32 v[126:127], v[126:127], v[184:185], v[152:153] op_sel_hi:[1,0,1]
	v_pk_fma_f32 v[124:125], v[124:125], v[184:185], v[154:155] op_sel_hi:[1,0,1]
	v_mul_f32_e32 v162, 0x45800000, v158
	v_cndmask_b32_e32 v172, v158, v162, vcc
	v_cmp_gt_f32_e32 vcc, s53, v179
	v_mul_f32_e32 v158, 0x4b800000, v179
	v_pk_fma_f32 v[120:121], v[120:121], v[184:185], v[150:151] op_sel_hi:[1,0,1]
	v_cndmask_b32_e32 v158, v179, v158, vcc
	v_rsq_f32_e32 v158, v158
	v_max_f32_e32 v122, 0, v122
	v_max_f32_e32 v124, 0, v124
	v_max_f32_e32 v120, 0, v120
	v_mul_f32_e32 v162, 0x45800000, v158
	v_cndmask_b32_e32 v158, v158, v162, vcc
	v_max_f32_e32 v121, 0, v121
	v_mul_f32_e32 v162, v122, v122
	v_max_f32_e32 v122, 0, v127
	v_mul_f32_e32 v124, v124, v124
	v_mul_f32_e32 v120, v120, v120
	v_max_f32_e32 v125, 0, v125
	v_mul_f32_e32 v121, v121, v121
	v_max_f32_e32 v126, 0, v126
	v_mul_f32_e32 v127, v122, v122
	v_max_f32_e32 v122, 0, v123
	v_mul_f32_e32 v125, v125, v125
	v_mul_f32_e32 v126, v126, v126
	v_mul_f32_e32 v164, v122, v122
	v_cvt_pk_bf16_f32 v122, v124, v125
	v_cvt_pk_bf16_f32 v123, v126, v127
	v_cvt_pk_bf16_f32 v124, v120, v121
	v_lshlrev_b64 v[120:121], 13, v[146:147]
	v_lshl_add_u64 v[120:121], s[8:9], 0, v[120:121]
	v_lshlrev_b64 v[126:127], 1, v[156:157]
	v_pk_fma_f32 v[114:115], v[114:115], v[182:183], v[148:149] op_sel_hi:[1,0,1]
	v_lshl_add_u64 v[120:121], v[120:121], 0, v[126:127]
	v_pk_fma_f32 v[118:119], v[118:119], v[182:183], v[152:153] op_sel_hi:[1,0,1]
	v_pk_fma_f32 v[116:117], v[116:117], v[182:183], v[154:155] op_sel_hi:[1,0,1]
	v_pk_fma_f32 v[112:113], v[112:113], v[182:183], v[150:151] op_sel_hi:[1,0,1]
	v_max_f32_e32 v114, 0, v114
	v_cvt_pk_bf16_f32 v125, v162, v164
	global_store_dwordx4 v[120:121], v[122:125], off
	v_max_f32_e32 v116, 0, v116
	v_max_f32_e32 v112, 0, v112
	v_mul_f32_e32 v122, v114, v114
	v_max_f32_e32 v114, 0, v119
	v_mul_f32_e32 v116, v116, v116
	v_mul_f32_e32 v112, v112, v112
	v_max_f32_e32 v117, 0, v117
	v_max_f32_e32 v113, 0, v113
	v_max_f32_e32 v118, 0, v118
	v_mul_f32_e32 v119, v114, v114
	v_max_f32_e32 v114, 0, v115
	v_mul_f32_e32 v117, v117, v117
	v_mul_f32_e32 v113, v113, v113
	v_mul_f32_e32 v118, v118, v118
	v_mul_f32_e32 v123, v114, v114
	v_cvt_pk_bf16_f32 v114, v116, v117
	v_cvt_pk_bf16_f32 v115, v118, v119
	v_cvt_pk_bf16_f32 v116, v112, v113
	v_or_b32_e32 v112, 16, v146
	v_ashrrev_i32_e32 v113, 31, v112
	v_lshlrev_b64 v[112:113], 13, v[112:113]
	v_lshl_add_u64 v[112:113], s[8:9], 0, v[112:113]
	v_pk_fma_f32 v[106:107], v[106:107], v[180:181], v[148:149] op_sel_hi:[1,0,1]
	v_lshl_add_u64 v[112:113], v[112:113], 0, v[126:127]
	v_pk_fma_f32 v[110:111], v[110:111], v[180:181], v[152:153] op_sel_hi:[1,0,1]
	v_pk_fma_f32 v[108:109], v[108:109], v[180:181], v[154:155] op_sel_hi:[1,0,1]
	v_pk_fma_f32 v[104:105], v[104:105], v[180:181], v[150:151] op_sel_hi:[1,0,1]
	v_max_f32_e32 v106, 0, v106
	v_cvt_pk_bf16_f32 v117, v122, v123
	global_store_dwordx4 v[112:113], v[114:117], off
	v_max_f32_e32 v108, 0, v108
	v_max_f32_e32 v104, 0, v104
	v_mul_f32_e32 v114, v106, v106
	v_max_f32_e32 v106, 0, v111
	v_mul_f32_e32 v108, v108, v108
	v_mul_f32_e32 v104, v104, v104
	v_max_f32_e32 v109, 0, v109
	v_max_f32_e32 v105, 0, v105
	v_max_f32_e32 v110, 0, v110
	v_mul_f32_e32 v111, v106, v106
	v_max_f32_e32 v106, 0, v107
	v_mul_f32_e32 v109, v109, v109
	v_mul_f32_e32 v105, v105, v105
	v_mul_f32_e32 v110, v110, v110
	v_mul_f32_e32 v115, v106, v106
	v_cvt_pk_bf16_f32 v106, v108, v109
	v_cvt_pk_bf16_f32 v107, v110, v111
	v_cvt_pk_bf16_f32 v108, v104, v105
	v_or_b32_e32 v104, 32, v146
	v_ashrrev_i32_e32 v105, 31, v104
	v_lshlrev_b64 v[104:105], 13, v[104:105]
	v_lshl_add_u64 v[104:105], s[8:9], 0, v[104:105]
	v_pk_fma_f32 v[98:99], v[98:99], v[178:179], v[148:149] op_sel_hi:[1,0,1]
	v_lshl_add_u64 v[104:105], v[104:105], 0, v[126:127]
	v_pk_fma_f32 v[102:103], v[102:103], v[178:179], v[152:153] op_sel_hi:[1,0,1]
	v_pk_fma_f32 v[100:101], v[100:101], v[178:179], v[154:155] op_sel_hi:[1,0,1]
	v_pk_fma_f32 v[96:97], v[96:97], v[178:179], v[150:151] op_sel_hi:[1,0,1]
	v_max_f32_e32 v98, 0, v98
	v_cvt_pk_bf16_f32 v109, v114, v115
	global_store_dwordx4 v[104:105], v[106:109], off
	v_max_f32_e32 v100, 0, v100
	v_max_f32_e32 v96, 0, v96
	v_mul_f32_e32 v106, v98, v98
	v_max_f32_e32 v98, 0, v103
	v_mul_f32_e32 v100, v100, v100
	v_mul_f32_e32 v96, v96, v96
	v_max_f32_e32 v101, 0, v101
	v_max_f32_e32 v97, 0, v97
	v_max_f32_e32 v102, 0, v102
	v_mul_f32_e32 v103, v98, v98
	v_max_f32_e32 v98, 0, v99
	v_mul_f32_e32 v101, v101, v101
	v_mul_f32_e32 v97, v97, v97
	v_mul_f32_e32 v102, v102, v102
	v_mul_f32_e32 v107, v98, v98
	v_cvt_pk_bf16_f32 v98, v100, v101
	v_cvt_pk_bf16_f32 v99, v102, v103
	v_cvt_pk_bf16_f32 v100, v96, v97
	v_or_b32_e32 v96, 48, v146
	v_ashrrev_i32_e32 v97, 31, v96
	v_lshlrev_b64 v[96:97], 13, v[96:97]
	v_lshl_add_u64 v[96:97], s[8:9], 0, v[96:97]
	v_pk_fma_f32 v[90:91], v[90:91], v[176:177], v[148:149] op_sel_hi:[1,0,1]
	v_lshl_add_u64 v[96:97], v[96:97], 0, v[126:127]
	v_pk_fma_f32 v[94:95], v[94:95], v[176:177], v[152:153] op_sel_hi:[1,0,1]
	v_max_f32_e32 v90, 0, v90
	v_cvt_pk_bf16_f32 v101, v106, v107
	global_store_dwordx4 v[96:97], v[98:101], off
	v_pk_fma_f32 v[92:93], v[92:93], v[176:177], v[154:155] op_sel_hi:[1,0,1]
	v_max_f32_e32 v94, 0, v94
	v_mul_f32_e32 v98, v90, v90
	v_max_f32_e32 v90, 0, v95
	v_max_f32_e32 v92, 0, v92
	v_max_f32_e32 v93, 0, v93
	v_mul_f32_e32 v94, v94, v94
	v_mul_f32_e32 v95, v90, v90
	v_max_f32_e32 v90, 0, v91
	v_pk_fma_f32 v[88:89], v[88:89], v[176:177], v[150:151] op_sel_hi:[1,0,1]
	v_mul_f32_e32 v92, v92, v92
	v_mul_f32_e32 v93, v93, v93
	v_mul_f32_e32 v99, v90, v90
	v_cvt_pk_bf16_f32 v90, v92, v93
	v_cvt_pk_bf16_f32 v91, v94, v95
	v_add_co_u32_e32 v94, vcc, s1, v120
	v_pk_fma_f32 v[82:83], v[82:83], v[174:175], v[148:149] op_sel_hi:[1,0,1]
	v_max_f32_e32 v88, 0, v88
	v_max_f32_e32 v89, 0, v89
	v_addc_co_u32_e32 v95, vcc, 0, v121, vcc
	v_pk_fma_f32 v[86:87], v[86:87], v[174:175], v[152:153] op_sel_hi:[1,0,1]
	v_max_f32_e32 v82, 0, v82
	v_mul_f32_e32 v88, v88, v88
	v_mul_f32_e32 v89, v89, v89
	v_cvt_pk_bf16_f32 v92, v88, v89
	v_cvt_pk_bf16_f32 v93, v98, v99
	global_store_dwordx4 v[94:95], v[90:93], off
	v_pk_fma_f32 v[84:85], v[84:85], v[174:175], v[154:155] op_sel_hi:[1,0,1]
	v_max_f32_e32 v86, 0, v86
	v_mul_f32_e32 v90, v82, v82
	v_max_f32_e32 v82, 0, v87
	v_max_f32_e32 v84, 0, v84
	v_max_f32_e32 v85, 0, v85
	v_mul_f32_e32 v86, v86, v86
	v_mul_f32_e32 v87, v82, v82
	v_max_f32_e32 v82, 0, v83
	s_mov_b32 s1, 0x120000
	v_pk_fma_f32 v[80:81], v[80:81], v[174:175], v[150:151] op_sel_hi:[1,0,1]
	v_mul_f32_e32 v84, v84, v84
	v_mul_f32_e32 v85, v85, v85
	v_mul_f32_e32 v91, v82, v82
	v_cvt_pk_bf16_f32 v82, v84, v85
	v_cvt_pk_bf16_f32 v83, v86, v87
	v_add_co_u32_e32 v86, vcc, s1, v120
	v_pk_fma_f32 v[74:75], v[74:75], v[172:173], v[148:149] op_sel_hi:[1,0,1]
	v_max_f32_e32 v80, 0, v80
	v_max_f32_e32 v81, 0, v81
	v_addc_co_u32_e32 v87, vcc, 0, v121, vcc
	v_pk_fma_f32 v[78:79], v[78:79], v[172:173], v[152:153] op_sel_hi:[1,0,1]
	v_max_f32_e32 v74, 0, v74
	v_mul_f32_e32 v80, v80, v80
	v_mul_f32_e32 v81, v81, v81
	v_cvt_pk_bf16_f32 v84, v80, v81
	v_cvt_pk_bf16_f32 v85, v90, v91
	global_store_dwordx4 v[86:87], v[82:85], off
	v_pk_fma_f32 v[76:77], v[76:77], v[172:173], v[154:155] op_sel_hi:[1,0,1]
	v_max_f32_e32 v78, 0, v78
	v_mul_f32_e32 v82, v74, v74
	v_max_f32_e32 v74, 0, v79
	v_max_f32_e32 v76, 0, v76
	v_max_f32_e32 v77, 0, v77
	v_mul_f32_e32 v78, v78, v78
	v_mul_f32_e32 v79, v74, v74
	v_max_f32_e32 v74, 0, v75
	s_mov_b32 s1, 0x140000
	v_pk_fma_f32 v[72:73], v[72:73], v[172:173], v[150:151] op_sel_hi:[1,0,1]
	v_mul_f32_e32 v76, v76, v76
	v_mul_f32_e32 v77, v77, v77
	v_mul_f32_e32 v83, v74, v74
	v_cvt_pk_bf16_f32 v74, v76, v77
	v_cvt_pk_bf16_f32 v75, v78, v79
	v_add_co_u32_e32 v78, vcc, s1, v120
	v_pk_fma_f32 v[58:59], v[58:59], v[158:159], v[148:149] op_sel_hi:[1,0,1]
	v_max_f32_e32 v72, 0, v72
	v_max_f32_e32 v73, 0, v73
	v_addc_co_u32_e32 v79, vcc, 0, v121, vcc
	v_pk_fma_f32 v[62:63], v[62:63], v[158:159], v[152:153] op_sel_hi:[1,0,1]
	v_max_f32_e32 v58, 0, v58
	v_mul_f32_e32 v72, v72, v72
	v_mul_f32_e32 v73, v73, v73
	v_cvt_pk_bf16_f32 v76, v72, v73
	v_cvt_pk_bf16_f32 v77, v82, v83
	global_store_dwordx4 v[78:79], v[74:77], off
	v_pk_fma_f32 v[60:61], v[60:61], v[158:159], v[154:155] op_sel_hi:[1,0,1]
	v_max_f32_e32 v62, 0, v62
	v_mul_f32_e32 v74, v58, v58
	v_max_f32_e32 v58, 0, v63
	v_max_f32_e32 v60, 0, v60
	v_max_f32_e32 v61, 0, v61
	v_mul_f32_e32 v62, v62, v62
	v_mul_f32_e32 v63, v58, v58
	v_max_f32_e32 v58, 0, v59
	s_mov_b32 s1, 0x160000
	v_pk_fma_f32 v[56:57], v[56:57], v[158:159], v[150:151] op_sel_hi:[1,0,1]
	v_mul_f32_e32 v60, v60, v60
	v_mul_f32_e32 v61, v61, v61
	v_mul_f32_e32 v75, v58, v58
	v_cvt_pk_bf16_f32 v58, v60, v61
	v_cvt_pk_bf16_f32 v59, v62, v63
	v_add_co_u32_e32 v62, vcc, s1, v120
	s_waitcnt vmcnt(7)
	v_pk_add_f32 v[134:135], v[134:135], 0 op_sel_hi:[1,0]
	v_max_f32_e32 v56, 0, v56
	v_max_f32_e32 v57, 0, v57
	v_addc_co_u32_e32 v63, vcc, 0, v121, vcc
	v_pk_add_f32 v[130:131], v[130:131], 0 op_sel_hi:[1,0]
	v_mul_f32_e32 v56, v56, v56
	v_mul_f32_e32 v57, v57, v57
	v_cvt_pk_bf16_f32 v60, v56, v57
	v_cvt_pk_bf16_f32 v61, v74, v75
	global_store_dwordx4 v[62:63], v[58:61], off
	v_pk_fma_f32 v[62:63], v[66:67], v[184:185], v[130:131] op_sel_hi:[1,0,1]
	v_pk_add_f32 v[132:133], v[132:133], 0 op_sel_hi:[1,0]
	v_pk_fma_f32 v[58:59], v[70:71], v[184:185], v[134:135] op_sel_hi:[1,0,1]
	v_pk_add_f32 v[128:129], v[128:129], 0 op_sel_hi:[1,0]
	v_max_f32_e32 v58, 0, v58
	v_mul_f32_e32 v66, v58, v58
	v_max_f32_e32 v58, 0, v62
	v_pk_fma_f32 v[60:61], v[68:69], v[184:185], v[132:133] op_sel_hi:[1,0,1]
	v_mul_f32_e32 v62, v58, v58
	v_max_f32_e32 v58, 0, v59
	v_pk_fma_f32 v[64:65], v[64:65], v[184:185], v[128:129] op_sel_hi:[1,0,1]
	v_max_f32_e32 v60, 0, v60
	v_max_f32_e32 v61, 0, v61
	v_mul_f32_e32 v59, v58, v58
	v_max_f32_e32 v58, 0, v63
	v_pk_fma_f32 v[48:49], v[48:49], v[182:183], v[128:129] op_sel_hi:[1,0,1]
	v_mul_f32_e32 v60, v60, v60
	v_max_f32_e32 v64, 0, v64
	v_mul_f32_e32 v61, v61, v61
	v_max_f32_e32 v65, 0, v65
	v_mul_f32_e32 v63, v58, v58
	v_cvt_pk_bf16_f32 v58, v60, v61
	v_pk_fma_f32 v[52:53], v[52:53], v[182:183], v[132:133] op_sel_hi:[1,0,1]
	v_pk_fma_f32 v[50:51], v[50:51], v[182:183], v[130:131] op_sel_hi:[1,0,1]
	v_max_f32_e32 v48, 0, v48
	v_mul_f32_e32 v64, v64, v64
	v_mul_f32_e32 v65, v65, v65
	v_cvt_pk_bf16_f32 v59, v66, v59
	v_cvt_pk_bf16_f32 v60, v64, v65
	v_cvt_pk_bf16_f32 v61, v62, v63
	global_store_dwordx4 v[120:121], v[58:61], off offset:256
	v_pk_fma_f32 v[54:55], v[54:55], v[182:183], v[134:135] op_sel_hi:[1,0,1]
	v_max_f32_e32 v49, 0, v49
	v_mul_f32_e32 v58, v48, v48
	v_max_f32_e32 v48, 0, v53
	v_max_f32_e32 v50, 0, v50
	v_max_f32_e32 v52, 0, v52
	v_mul_f32_e32 v48, v48, v48
	v_mul_f32_e32 v53, v49, v49
	v_max_f32_e32 v49, 0, v54
	v_mul_f32_e32 v54, v50, v50
	v_max_f32_e32 v50, 0, v55
	v_max_f32_e32 v51, 0, v51
	v_pk_fma_f32 v[40:41], v[40:41], v[180:181], v[128:129] op_sel_hi:[1,0,1]
	v_mul_f32_e32 v52, v52, v52
	v_mul_f32_e32 v49, v49, v49
	v_mul_f32_e32 v50, v50, v50
	v_mul_f32_e32 v51, v51, v51
	v_cvt_pk_bf16_f32 v48, v52, v48
	v_pk_fma_f32 v[44:45], v[44:45], v[180:181], v[132:133] op_sel_hi:[1,0,1]
	v_pk_fma_f32 v[42:43], v[42:43], v[180:181], v[130:131] op_sel_hi:[1,0,1]
	v_max_f32_e32 v40, 0, v40
	v_cvt_pk_bf16_f32 v49, v49, v50
	v_cvt_pk_bf16_f32 v50, v58, v53
	v_cvt_pk_bf16_f32 v51, v54, v51
	global_store_dwordx4 v[112:113], v[48:51], off offset:256
	v_pk_fma_f32 v[46:47], v[46:47], v[180:181], v[134:135] op_sel_hi:[1,0,1]
	v_max_f32_e32 v41, 0, v41
	v_mul_f32_e32 v48, v40, v40
	v_max_f32_e32 v40, 0, v45
	v_max_f32_e32 v42, 0, v42
	v_max_f32_e32 v44, 0, v44
	v_mul_f32_e32 v40, v40, v40
	v_mul_f32_e32 v45, v41, v41
	v_max_f32_e32 v41, 0, v46
	v_mul_f32_e32 v46, v42, v42
	v_max_f32_e32 v42, 0, v47
	v_max_f32_e32 v43, 0, v43
	v_pk_fma_f32 v[32:33], v[32:33], v[178:179], v[128:129] op_sel_hi:[1,0,1]
	v_mul_f32_e32 v44, v44, v44
	v_mul_f32_e32 v41, v41, v41
	v_mul_f32_e32 v42, v42, v42
	v_mul_f32_e32 v43, v43, v43
	v_cvt_pk_bf16_f32 v40, v44, v40
	v_pk_fma_f32 v[36:37], v[36:37], v[178:179], v[132:133] op_sel_hi:[1,0,1]
	v_pk_fma_f32 v[34:35], v[34:35], v[178:179], v[130:131] op_sel_hi:[1,0,1]
	v_max_f32_e32 v32, 0, v32
	v_cvt_pk_bf16_f32 v41, v41, v42
	v_cvt_pk_bf16_f32 v42, v48, v45
	v_cvt_pk_bf16_f32 v43, v46, v43
	global_store_dwordx4 v[104:105], v[40:43], off offset:256
	v_pk_fma_f32 v[38:39], v[38:39], v[178:179], v[134:135] op_sel_hi:[1,0,1]
	v_max_f32_e32 v33, 0, v33
	v_mul_f32_e32 v40, v32, v32
	v_max_f32_e32 v32, 0, v37
	v_max_f32_e32 v34, 0, v34
	v_max_f32_e32 v36, 0, v36
	v_mul_f32_e32 v32, v32, v32
	v_mul_f32_e32 v37, v33, v33
	v_max_f32_e32 v33, 0, v38
	v_mul_f32_e32 v38, v34, v34
	v_max_f32_e32 v34, 0, v39
	v_max_f32_e32 v35, 0, v35
	v_pk_fma_f32 v[24:25], v[24:25], v[176:177], v[128:129] op_sel_hi:[1,0,1]
	v_mul_f32_e32 v36, v36, v36
	v_mul_f32_e32 v33, v33, v33
	v_mul_f32_e32 v34, v34, v34
	v_mul_f32_e32 v35, v35, v35
	v_cvt_pk_bf16_f32 v32, v36, v32
	v_pk_fma_f32 v[28:29], v[28:29], v[176:177], v[132:133] op_sel_hi:[1,0,1]
	v_pk_fma_f32 v[26:27], v[26:27], v[176:177], v[130:131] op_sel_hi:[1,0,1]
	v_max_f32_e32 v24, 0, v24
	v_cvt_pk_bf16_f32 v33, v33, v34
	v_cvt_pk_bf16_f32 v34, v40, v37
	v_cvt_pk_bf16_f32 v35, v38, v35
	global_store_dwordx4 v[96:97], v[32:35], off offset:256
	v_pk_fma_f32 v[30:31], v[30:31], v[176:177], v[134:135] op_sel_hi:[1,0,1]
	v_max_f32_e32 v25, 0, v25
	v_mul_f32_e32 v32, v24, v24
	v_max_f32_e32 v24, 0, v29
	v_max_f32_e32 v26, 0, v26
	s_mov_b64 s[8:9], 0x100000
	v_max_f32_e32 v28, 0, v28
	v_mul_f32_e32 v24, v24, v24
	v_mul_f32_e32 v29, v25, v25
	v_max_f32_e32 v25, 0, v30
	v_mul_f32_e32 v30, v26, v26
	v_max_f32_e32 v26, 0, v31
	v_max_f32_e32 v27, 0, v27
	v_pk_fma_f32 v[16:17], v[16:17], v[174:175], v[128:129] op_sel_hi:[1,0,1]
	v_lshl_add_u64 v[88:89], v[120:121], 0, s[8:9]
	v_mul_f32_e32 v28, v28, v28
	v_mul_f32_e32 v25, v25, v25
	v_mul_f32_e32 v26, v26, v26
	v_mul_f32_e32 v27, v27, v27
	v_cvt_pk_bf16_f32 v24, v28, v24
	v_pk_fma_f32 v[20:21], v[20:21], v[174:175], v[132:133] op_sel_hi:[1,0,1]
	v_pk_fma_f32 v[18:19], v[18:19], v[174:175], v[130:131] op_sel_hi:[1,0,1]
	v_max_f32_e32 v16, 0, v16
	v_cvt_pk_bf16_f32 v25, v25, v26
	v_cvt_pk_bf16_f32 v26, v32, v29
	v_cvt_pk_bf16_f32 v27, v30, v27
	global_store_dwordx4 v[88:89], v[24:27], off offset:256
	v_pk_fma_f32 v[22:23], v[22:23], v[174:175], v[134:135] op_sel_hi:[1,0,1]
	v_max_f32_e32 v17, 0, v17
	v_mul_f32_e32 v24, v16, v16
	v_max_f32_e32 v16, 0, v21
	v_max_f32_e32 v18, 0, v18
	s_mov_b64 s[8:9], 0x120000
	v_max_f32_e32 v20, 0, v20
	v_mul_f32_e32 v16, v16, v16
	v_mul_f32_e32 v21, v17, v17
	v_max_f32_e32 v17, 0, v22
	v_mul_f32_e32 v22, v18, v18
	v_max_f32_e32 v18, 0, v23
	v_max_f32_e32 v19, 0, v19
	v_pk_fma_f32 v[8:9], v[8:9], v[172:173], v[128:129] op_sel_hi:[1,0,1]
	v_lshl_add_u64 v[80:81], v[120:121], 0, s[8:9]
	v_mul_f32_e32 v20, v20, v20
	v_mul_f32_e32 v17, v17, v17
	v_mul_f32_e32 v18, v18, v18
	v_mul_f32_e32 v19, v19, v19
	v_cvt_pk_bf16_f32 v16, v20, v16
	v_pk_fma_f32 v[12:13], v[12:13], v[172:173], v[132:133] op_sel_hi:[1,0,1]
	v_pk_fma_f32 v[10:11], v[10:11], v[172:173], v[130:131] op_sel_hi:[1,0,1]
	v_max_f32_e32 v8, 0, v8
	v_cvt_pk_bf16_f32 v17, v17, v18
	v_cvt_pk_bf16_f32 v18, v24, v21
	v_cvt_pk_bf16_f32 v19, v22, v19
	global_store_dwordx4 v[80:81], v[16:19], off offset:256
	v_pk_fma_f32 v[14:15], v[14:15], v[172:173], v[134:135] op_sel_hi:[1,0,1]
	v_max_f32_e32 v9, 0, v9
	v_mul_f32_e32 v16, v8, v8
	v_max_f32_e32 v8, 0, v13
	v_max_f32_e32 v10, 0, v10
	s_mov_b64 s[8:9], 0x140000
	v_max_f32_e32 v12, 0, v12
	v_mul_f32_e32 v8, v8, v8
	v_mul_f32_e32 v13, v9, v9
	v_max_f32_e32 v9, 0, v14
	v_mul_f32_e32 v14, v10, v10
	v_max_f32_e32 v10, 0, v15
	v_max_f32_e32 v11, 0, v11
	v_pk_fma_f32 v[2:3], v[2:3], v[158:159], v[130:131] op_sel_hi:[1,0,1]
	v_pk_fma_f32 v[0:1], v[0:1], v[158:159], v[128:129] op_sel_hi:[1,0,1]
	v_lshl_add_u64 v[72:73], v[120:121], 0, s[8:9]
	v_mul_f32_e32 v12, v12, v12
	v_mul_f32_e32 v9, v9, v9
	v_mul_f32_e32 v10, v10, v10
	v_mul_f32_e32 v11, v11, v11
	v_cvt_pk_bf16_f32 v8, v12, v8
	v_pk_fma_f32 v[6:7], v[6:7], v[158:159], v[134:135] op_sel_hi:[1,0,1]
	v_pk_fma_f32 v[4:5], v[4:5], v[158:159], v[132:133] op_sel_hi:[1,0,1]
	v_max_f32_e32 v0, 0, v0
	v_max_f32_e32 v1, 0, v1
	v_max_f32_e32 v2, 0, v2
	s_mov_b64 s[8:9], 0x160000
	v_cvt_pk_bf16_f32 v9, v9, v10
	v_cvt_pk_bf16_f32 v10, v16, v13
	v_cvt_pk_bf16_f32 v11, v14, v11
	global_store_dwordx4 v[72:73], v[8:11], off offset:256
	v_max_f32_e32 v3, 0, v3
	v_lshl_add_u64 v[56:57], v[120:121], 0, s[8:9]
	v_mul_f32_e32 v8, v0, v0
	v_max_f32_e32 v0, 0, v5
	v_mul_f32_e32 v5, v1, v1
	v_max_f32_e32 v1, 0, v6
	v_mul_f32_e32 v6, v2, v2
	v_max_f32_e32 v2, 0, v7
	v_max_f32_e32 v4, 0, v4
	v_mul_f32_e32 v0, v0, v0
	v_mul_f32_e32 v1, v1, v1
	v_mul_f32_e32 v2, v2, v2
	v_mul_f32_e32 v3, v3, v3
	s_and_b64 vcc, exec, s[2:3]
	s_mov_b64 s[8:9], s[58:59]
	v_mul_f32_e32 v4, v4, v4
	v_cvt_pk_bf16_f32 v0, v4, v0
	v_cvt_pk_bf16_f32 v1, v1, v2
	v_cvt_pk_bf16_f32 v2, v8, v5
	v_cvt_pk_bf16_f32 v3, v6, v3
	global_store_dwordx4 v[56:57], v[0:3], off offset:256
	s_cbranch_vccz .LBB0_123
	s_waitcnt vmcnt(0)
	s_mov_b32 s90, s62
	s_cmpk_gt_u32 s36, 0xff
	s_cbranch_scc1 .LBB0_134
	s_barrier

.LBB0_350:
	s_add_u32 s8, s60, 0xfffc0080
	s_addc_u32 s9, s61, -1
	s_add_i32 s16, 0, 0x10000
	v_add_u32_e32 v150, s16, v168
	ds_read_b128 v[128:131], v150
	ds_read_b128 v[132:135], v150 offset:1024
	ds_read_b128 v[146:149], v150 offset:2048
	ds_read_b128 v[150:153], v150 offset:3072
	s_cmp_eq_u32 s15, 12
	s_cselect_b32 s9, s5, s9
	s_cselect_b32 s8, s10, s8
	s_cselect_b32 s63, s1, s14
	s_cselect_b32 s62, s12, s13
	v_lshl_add_u64 v[200:201], s[60:61], 0, v[142:143]
	s_add_i32 m0, s38, 0xc000
	ds_read_b128 v[154:157], v170
	ds_read_b128 v[172:175], v170 offset:1024
	ds_read_b128 v[176:179], v170 offset:2048
	ds_read_b128 v[180:183], v170 offset:3072
	ds_read_b128 v[184:187], v170 offset:4096
	ds_read_b128 v[188:191], v170 offset:5120
	ds_read_b128 v[192:195], v170 offset:6144
	ds_read_b128 v[196:199], v170 offset:7168
	global_load_lds_dwordx4 v[200:201], off
	v_lshl_add_u64 v[200:201], s[60:61], 0, v[144:145]
	s_add_i32 m0, s38, 0xe000
	s_nop 0
	global_load_lds_dwordx4 v[200:201], off
	s_waitcnt lgkmcnt(8)
	s_barrier
	s_waitcnt lgkmcnt(0)
	s_setprio 1
	s_waitcnt lgkmcnt(0)
	v_mfma_f32_16x16x32_bf16 v[124:127], v[128:131], v[154:157], v[124:127]
	v_mfma_f32_16x16x32_bf16 v[120:123], v[146:149], v[154:157], v[120:123]
	v_mfma_f32_16x16x32_bf16 v[116:119], v[128:131], v[176:179], v[116:119]
	v_mfma_f32_16x16x32_bf16 v[112:115], v[146:149], v[176:179], v[112:115]
	v_mfma_f32_16x16x32_bf16 v[108:111], v[128:131], v[184:187], v[108:111]
	v_mfma_f32_16x16x32_bf16 v[104:107], v[146:149], v[184:187], v[104:107]
	v_mfma_f32_16x16x32_bf16 v[100:103], v[128:131], v[192:195], v[100:103]
	v_mfma_f32_16x16x32_bf16 v[96:99], v[146:149], v[192:195], v[96:99]
	v_mfma_f32_16x16x32_bf16 v[124:127], v[132:135], v[172:175], v[124:127]
	v_mfma_f32_16x16x32_bf16 v[120:123], v[150:153], v[172:175], v[120:123]
	v_mfma_f32_16x16x32_bf16 v[116:119], v[132:135], v[180:183], v[116:119]
	v_mfma_f32_16x16x32_bf16 v[112:115], v[150:153], v[180:183], v[112:115]
	v_mfma_f32_16x16x32_bf16 v[108:111], v[132:135], v[188:191], v[108:111]
	v_mfma_f32_16x16x32_bf16 v[104:107], v[150:153], v[188:191], v[104:107]
	v_mfma_f32_16x16x32_bf16 v[100:103], v[132:135], v[196:199], v[100:103]
	v_mfma_f32_16x16x32_bf16 v[96:99], v[150:153], v[196:199], v[96:99]
	s_setprio 0
	s_barrier
	s_add_i32 s18, 0, 0x14000
	s_add_i32 s16, s16, s37
	v_add_u32_e32 v158, s18, v168
	v_lshl_add_u64 v[216:217], s[62:63], 0, v[160:161]
	s_mov_b32 m0, s16
	ds_read_b128 v[200:203], v158
	ds_read_b128 v[204:207], v158 offset:1024
	ds_read_b128 v[208:211], v158 offset:2048
	ds_read_b128 v[212:215], v158 offset:3072
	global_load_lds_dwordx4 v[216:217], off
	v_lshl_add_u64 v[218:219], s[62:63], 0, v[136:137]
	s_add_i32 m0, s16, 0x2000
	s_nop 0
	global_load_lds_dwordx4 v[218:219], off
	s_barrier
	s_waitcnt lgkmcnt(0)
	s_setprio 1
	s_waitcnt lgkmcnt(0)
	v_mfma_f32_16x16x32_bf16 v[68:71], v[200:203], v[154:157], v[68:71]
	v_mfma_f32_16x16x32_bf16 v[64:67], v[208:211], v[154:157], v[64:67]
	v_mfma_f32_16x16x32_bf16 v[52:55], v[200:203], v[176:179], v[52:55]
	v_mfma_f32_16x16x32_bf16 v[48:51], v[208:211], v[176:179], v[48:51]
	v_mfma_f32_16x16x32_bf16 v[44:47], v[200:203], v[184:187], v[44:47]
	v_mfma_f32_16x16x32_bf16 v[40:43], v[208:211], v[184:187], v[40:43]
	v_mfma_f32_16x16x32_bf16 v[36:39], v[200:203], v[192:195], v[36:39]
	v_mfma_f32_16x16x32_bf16 v[32:35], v[208:211], v[192:195], v[32:35]
	v_mfma_f32_16x16x32_bf16 v[68:71], v[204:207], v[172:175], v[68:71]
	v_mfma_f32_16x16x32_bf16 v[64:67], v[212:215], v[172:175], v[64:67]
	v_mfma_f32_16x16x32_bf16 v[52:55], v[204:207], v[180:183], v[52:55]
	v_mfma_f32_16x16x32_bf16 v[48:51], v[212:215], v[180:183], v[48:51]
	v_mfma_f32_16x16x32_bf16 v[44:47], v[204:207], v[188:191], v[44:47]
	v_mfma_f32_16x16x32_bf16 v[40:43], v[212:215], v[188:191], v[40:43]
	v_mfma_f32_16x16x32_bf16 v[36:39], v[204:207], v[196:199], v[36:39]
	v_mfma_f32_16x16x32_bf16 v[32:35], v[212:215], v[196:199], v[32:35]
	s_setprio 0
	s_mov_b32 m0, s38
	v_lshl_add_u64 v[220:221], s[8:9], 0, v[140:141]
	s_barrier
	ds_read_b128 v[154:157], v170 offset:16384
	ds_read_b128 v[172:175], v170 offset:17408
	ds_read_b128 v[176:179], v170 offset:18432
	ds_read_b128 v[180:183], v170 offset:19456
	ds_read_b128 v[184:187], v170 offset:20480
	ds_read_b128 v[188:191], v170 offset:21504
	ds_read_b128 v[192:195], v170 offset:22528
	ds_read_b128 v[196:199], v170 offset:23552
	global_load_lds_dwordx4 v[220:221], off
	v_lshl_add_u64 v[222:223], s[8:9], 0, v[138:139]
	s_mov_b32 m0, s39
	s_nop 0
	global_load_lds_dwordx4 v[222:223], off
	s_barrier
	s_waitcnt lgkmcnt(0)
	s_setprio 1
	s_waitcnt lgkmcnt(0)
	v_mfma_f32_16x16x32_bf16 v[92:95], v[128:131], v[154:157], v[92:95]
	v_mfma_f32_16x16x32_bf16 v[88:91], v[146:149], v[154:157], v[88:91]
	v_mfma_f32_16x16x32_bf16 v[84:87], v[128:131], v[176:179], v[84:87]
	v_mfma_f32_16x16x32_bf16 v[80:83], v[146:149], v[176:179], v[80:83]
	v_mfma_f32_16x16x32_bf16 v[76:79], v[128:131], v[184:187], v[76:79]
	v_mfma_f32_16x16x32_bf16 v[72:75], v[146:149], v[184:187], v[72:75]
	v_mfma_f32_16x16x32_bf16 v[60:63], v[128:131], v[192:195], v[60:63]
	v_mfma_f32_16x16x32_bf16 v[56:59], v[146:149], v[192:195], v[56:59]
	v_mfma_f32_16x16x32_bf16 v[92:95], v[132:135], v[172:175], v[92:95]
	v_mfma_f32_16x16x32_bf16 v[88:91], v[150:153], v[172:175], v[88:91]
	v_mfma_f32_16x16x32_bf16 v[84:87], v[132:135], v[180:183], v[84:87]
	v_mfma_f32_16x16x32_bf16 v[80:83], v[150:153], v[180:183], v[80:83]
	v_mfma_f32_16x16x32_bf16 v[76:79], v[132:135], v[188:191], v[76:79]
	v_mfma_f32_16x16x32_bf16 v[72:75], v[150:153], v[188:191], v[72:75]
	v_mfma_f32_16x16x32_bf16 v[60:63], v[132:135], v[196:199], v[60:63]
	v_mfma_f32_16x16x32_bf16 v[56:59], v[150:153], v[196:199], v[56:59]
	s_setprio 0
	s_barrier
	s_add_u32 s16, s62, 0x40000
	s_addc_u32 s17, s63, 0
	s_add_i32 s18, s18, s37
	v_lshl_add_u64 v[128:129], s[16:17], 0, v[160:161]
	s_mov_b32 m0, s18
	s_nop 0
	global_load_lds_dwordx4 v[128:129], off
	v_lshl_add_u64 v[128:129], s[16:17], 0, v[136:137]
	s_add_i32 m0, s18, 0x2000
	s_nop 0
	global_load_lds_dwordx4 v[128:129], off
	s_waitcnt vmcnt(6)
	s_barrier
	s_setprio 1
	v_mfma_f32_16x16x32_bf16 v[28:31], v[200:203], v[154:157], v[28:31]
	v_mfma_f32_16x16x32_bf16 v[24:27], v[208:211], v[154:157], v[24:27]
	v_mfma_f32_16x16x32_bf16 v[20:23], v[200:203], v[176:179], v[20:23]
	v_mfma_f32_16x16x32_bf16 v[16:19], v[208:211], v[176:179], v[16:19]
	v_mfma_f32_16x16x32_bf16 v[12:15], v[200:203], v[184:187], v[12:15]
	v_mfma_f32_16x16x32_bf16 v[8:11], v[208:211], v[184:187], v[8:11]
	v_mfma_f32_16x16x32_bf16 v[4:7], v[200:203], v[192:195], v[4:7]
	v_mfma_f32_16x16x32_bf16 v[0:3], v[208:211], v[192:195], v[0:3]
	v_mfma_f32_16x16x32_bf16 v[28:31], v[204:207], v[172:175], v[28:31]
	v_mfma_f32_16x16x32_bf16 v[24:27], v[212:215], v[172:175], v[24:27]
	v_mfma_f32_16x16x32_bf16 v[20:23], v[204:207], v[180:183], v[20:23]
	v_mfma_f32_16x16x32_bf16 v[16:19], v[212:215], v[180:183], v[16:19]
	v_mfma_f32_16x16x32_bf16 v[12:15], v[204:207], v[188:191], v[12:15]
	v_mfma_f32_16x16x32_bf16 v[8:11], v[212:215], v[188:191], v[8:11]
	v_mfma_f32_16x16x32_bf16 v[4:7], v[204:207], v[196:199], v[4:7]
	v_mfma_f32_16x16x32_bf16 v[0:3], v[212:215], v[196:199], v[0:3]
	s_setprio 0
	s_add_i32 s16, 0, 0x18000
	v_add_u32_e32 v150, s16, v168
	s_barrier
	ds_read_b128 v[128:131], v150
	ds_read_b128 v[132:135], v150 offset:1024
	ds_read_b128 v[146:149], v150 offset:2048
	ds_read_b128 v[150:153], v150 offset:3072
	s_add_u32 s8, s8, 0x40000
	s_addc_u32 s9, s9, 0
	s_mov_b32 m0, s40
	v_lshl_add_u64 v[200:201], s[8:9], 0, v[140:141]
	ds_read_b128 v[154:157], v170 offset:32768
	ds_read_b128 v[172:175], v170 offset:33792
	ds_read_b128 v[176:179], v170 offset:34816
	ds_read_b128 v[180:183], v170 offset:35840
	ds_read_b128 v[184:187], v170 offset:36864
	ds_read_b128 v[188:191], v170 offset:37888
	ds_read_b128 v[192:195], v170 offset:38912
	ds_read_b128 v[196:199], v170 offset:39936
	global_load_lds_dwordx4 v[200:201], off
	v_lshl_add_u64 v[200:201], s[8:9], 0, v[138:139]
	s_mov_b32 m0, s41
	s_nop 0
	global_load_lds_dwordx4 v[200:201], off
	s_waitcnt lgkmcnt(8)
	s_barrier
	s_waitcnt lgkmcnt(0)
	s_setprio 1
	s_waitcnt lgkmcnt(0)
	v_mfma_f32_16x16x32_bf16 v[124:127], v[128:131], v[154:157], v[124:127]
	v_mfma_f32_16x16x32_bf16 v[120:123], v[146:149], v[154:157], v[120:123]
	v_mfma_f32_16x16x32_bf16 v[116:119], v[128:131], v[176:179], v[116:119]
	v_mfma_f32_16x16x32_bf16 v[112:115], v[146:149], v[176:179], v[112:115]
	v_mfma_f32_16x16x32_bf16 v[108:111], v[128:131], v[184:187], v[108:111]
	v_mfma_f32_16x16x32_bf16 v[104:107], v[146:149], v[184:187], v[104:107]
	v_mfma_f32_16x16x32_bf16 v[100:103], v[128:131], v[192:195], v[100:103]
	v_mfma_f32_16x16x32_bf16 v[96:99], v[146:149], v[192:195], v[96:99]
	v_mfma_f32_16x16x32_bf16 v[124:127], v[132:135], v[172:175], v[124:127]
	v_mfma_f32_16x16x32_bf16 v[120:123], v[150:153], v[172:175], v[120:123]
	v_mfma_f32_16x16x32_bf16 v[116:119], v[132:135], v[180:183], v[116:119]
	v_mfma_f32_16x16x32_bf16 v[112:115], v[150:153], v[180:183], v[112:115]
	v_mfma_f32_16x16x32_bf16 v[108:111], v[132:135], v[188:191], v[108:111]
	v_mfma_f32_16x16x32_bf16 v[104:107], v[150:153], v[188:191], v[104:107]
	v_mfma_f32_16x16x32_bf16 v[100:103], v[132:135], v[196:199], v[100:103]
	v_mfma_f32_16x16x32_bf16 v[96:99], v[150:153], v[196:199], v[96:99]
	s_setprio 0
	s_barrier
	s_add_i32 s17, 0, 0x1c000
	s_add_i32 s8, s16, s37
	v_add_u32_e32 v158, s17, v168
	v_lshl_add_u64 v[216:217], v[216:217], 0, s[74:75]
	s_mov_b32 m0, s8
	ds_read_b128 v[200:203], v158
	ds_read_b128 v[204:207], v158 offset:1024
	ds_read_b128 v[208:211], v158 offset:2048
	ds_read_b128 v[212:215], v158 offset:3072
	global_load_lds_dwordx4 v[216:217], off
	v_lshl_add_u64 v[216:217], v[218:219], 0, s[74:75]
	s_add_i32 m0, s8, 0x2000
	s_nop 0
	global_load_lds_dwordx4 v[216:217], off
	s_barrier
	s_waitcnt lgkmcnt(0)
	s_setprio 1
	s_waitcnt lgkmcnt(0)
	v_mfma_f32_16x16x32_bf16 v[68:71], v[200:203], v[154:157], v[68:71]
	v_mfma_f32_16x16x32_bf16 v[64:67], v[208:211], v[154:157], v[64:67]
	v_mfma_f32_16x16x32_bf16 v[52:55], v[200:203], v[176:179], v[52:55]
	v_mfma_f32_16x16x32_bf16 v[48:51], v[208:211], v[176:179], v[48:51]
	v_mfma_f32_16x16x32_bf16 v[44:47], v[200:203], v[184:187], v[44:47]
	v_mfma_f32_16x16x32_bf16 v[40:43], v[208:211], v[184:187], v[40:43]
	v_mfma_f32_16x16x32_bf16 v[36:39], v[200:203], v[192:195], v[36:39]
	v_mfma_f32_16x16x32_bf16 v[32:35], v[208:211], v[192:195], v[32:35]
	v_mfma_f32_16x16x32_bf16 v[68:71], v[204:207], v[172:175], v[68:71]
	v_mfma_f32_16x16x32_bf16 v[64:67], v[212:215], v[172:175], v[64:67]
	v_mfma_f32_16x16x32_bf16 v[52:55], v[204:207], v[180:183], v[52:55]
	v_mfma_f32_16x16x32_bf16 v[48:51], v[212:215], v[180:183], v[48:51]
	v_mfma_f32_16x16x32_bf16 v[44:47], v[204:207], v[188:191], v[44:47]
	v_mfma_f32_16x16x32_bf16 v[40:43], v[212:215], v[188:191], v[40:43]
	v_mfma_f32_16x16x32_bf16 v[36:39], v[204:207], v[196:199], v[36:39]
	v_mfma_f32_16x16x32_bf16 v[32:35], v[212:215], v[196:199], v[32:35]
	s_setprio 0
	s_mov_b32 m0, s42
	v_lshl_add_u64 v[216:217], v[220:221], 0, s[74:75]
	s_barrier
	ds_read_b128 v[154:157], v170 offset:49152
	ds_read_b128 v[172:175], v170 offset:50176
	ds_read_b128 v[176:179], v170 offset:51200
	ds_read_b128 v[180:183], v170 offset:52224
	ds_read_b128 v[184:187], v170 offset:53248
	ds_read_b128 v[188:191], v170 offset:54272
	ds_read_b128 v[192:195], v170 offset:55296
	ds_read_b128 v[196:199], v170 offset:56320
	global_load_lds_dwordx4 v[216:217], off
	v_lshl_add_u64 v[216:217], v[222:223], 0, s[74:75]
	s_mov_b32 m0, s43
	s_nop 0
	global_load_lds_dwordx4 v[216:217], off
	s_barrier
	s_waitcnt lgkmcnt(0)
	s_setprio 1
	s_waitcnt lgkmcnt(0)
	v_mfma_f32_16x16x32_bf16 v[92:95], v[128:131], v[154:157], v[92:95]
	v_mfma_f32_16x16x32_bf16 v[88:91], v[146:149], v[154:157], v[88:91]
	v_mfma_f32_16x16x32_bf16 v[84:87], v[128:131], v[176:179], v[84:87]
	v_mfma_f32_16x16x32_bf16 v[80:83], v[146:149], v[176:179], v[80:83]
	v_mfma_f32_16x16x32_bf16 v[76:79], v[128:131], v[184:187], v[76:79]
	v_mfma_f32_16x16x32_bf16 v[72:75], v[146:149], v[184:187], v[72:75]
	v_mfma_f32_16x16x32_bf16 v[60:63], v[128:131], v[192:195], v[60:63]
	v_mfma_f32_16x16x32_bf16 v[56:59], v[146:149], v[192:195], v[56:59]
	v_mfma_f32_16x16x32_bf16 v[92:95], v[132:135], v[172:175], v[92:95]
	v_mfma_f32_16x16x32_bf16 v[88:91], v[150:153], v[172:175], v[88:91]
	v_mfma_f32_16x16x32_bf16 v[84:87], v[132:135], v[180:183], v[84:87]
	v_mfma_f32_16x16x32_bf16 v[80:83], v[150:153], v[180:183], v[80:83]
	v_mfma_f32_16x16x32_bf16 v[76:79], v[132:135], v[188:191], v[76:79]
	v_mfma_f32_16x16x32_bf16 v[72:75], v[150:153], v[188:191], v[72:75]
	v_mfma_f32_16x16x32_bf16 v[60:63], v[132:135], v[196:199], v[60:63]
	v_mfma_f32_16x16x32_bf16 v[56:59], v[150:153], v[196:199], v[56:59]
	s_setprio 0
	s_barrier
	s_add_u32 s8, s62, 0x40080
	s_addc_u32 s9, s63, 0
	s_add_i32 s16, s17, s37
	v_lshl_add_u64 v[128:129], s[8:9], 0, v[160:161]
	s_mov_b32 m0, s16
	s_nop 0
	global_load_lds_dwordx4 v[128:129], off
	v_lshl_add_u64 v[128:129], s[8:9], 0, v[136:137]
	s_add_i32 m0, s16, 0x2000
	s_nop 0
	global_load_lds_dwordx4 v[128:129], off
	s_waitcnt vmcnt(6)
	s_barrier
	s_setprio 1
	v_mfma_f32_16x16x32_bf16 v[28:31], v[200:203], v[154:157], v[28:31]
	v_mfma_f32_16x16x32_bf16 v[24:27], v[208:211], v[154:157], v[24:27]
	v_mfma_f32_16x16x32_bf16 v[20:23], v[200:203], v[176:179], v[20:23]
	v_mfma_f32_16x16x32_bf16 v[16:19], v[208:211], v[176:179], v[16:19]
	v_mfma_f32_16x16x32_bf16 v[12:15], v[200:203], v[184:187], v[12:15]
	v_mfma_f32_16x16x32_bf16 v[8:11], v[208:211], v[184:187], v[8:11]
	v_mfma_f32_16x16x32_bf16 v[4:7], v[200:203], v[192:195], v[4:7]
	v_mfma_f32_16x16x32_bf16 v[0:3], v[208:211], v[192:195], v[0:3]
	v_mfma_f32_16x16x32_bf16 v[28:31], v[204:207], v[172:175], v[28:31]
	v_mfma_f32_16x16x32_bf16 v[24:27], v[212:215], v[172:175], v[24:27]
	v_mfma_f32_16x16x32_bf16 v[20:23], v[204:207], v[180:183], v[20:23]
	v_mfma_f32_16x16x32_bf16 v[16:19], v[212:215], v[180:183], v[16:19]
	v_mfma_f32_16x16x32_bf16 v[12:15], v[204:207], v[188:191], v[12:15]
	v_mfma_f32_16x16x32_bf16 v[8:11], v[212:215], v[188:191], v[8:11]
	v_mfma_f32_16x16x32_bf16 v[4:7], v[204:207], v[196:199], v[4:7]
	v_mfma_f32_16x16x32_bf16 v[0:3], v[212:215], v[196:199], v[0:3]
	s_setprio 0
	s_add_i32 s15, s15, 2
	s_add_u32 s60, s60, 0x100
	s_addc_u32 s61, s61, 0
	s_add_u32 s13, s13, 0x100
	s_addc_u32 s14, s14, 0
	s_cmp_gt_u32 s15, 13
	s_barrier
	s_cbranch_scc0 .LBB0_350
	v_lshl_add_u32 v146, s65, 8, v159
	v_readlane_b32 s8, v249, 24
	v_ashrrev_i32_e32 v147, 31, v146
	v_readlane_b32 s9, v249, 25
	v_readlane_b32 s12, v249, 26
	v_lshl_or_b32 v156, s66, 8, v169
	v_lshl_add_u64 v[128:129], v[146:147], 3, s[8:9]
	global_load_dwordx2 v[130:131], v[128:129], off
	global_load_dwordx2 v[218:219], v[128:129], off offset:128
	global_load_dwordx2 v[220:221], v[128:129], off offset:256
	global_load_dwordx2 v[222:223], v[128:129], off offset:384
	global_load_dwordx2 v[224:225], v[128:129], off offset:1024
	global_load_dwordx2 v[226:227], v[128:129], off offset:1152
	global_load_dwordx2 v[228:229], v[128:129], off offset:1280
	global_load_dwordx2 v[230:231], v[128:129], off offset:1408
	s_ashr_i32 s8, s65, 5
	s_ashr_i32 s9, s8, 31
	s_lshl_b64 s[8:9], s[8:9], 14
	v_readlane_b32 s13, v249, 27
	s_add_u32 s8, s12, s8
	v_ashrrev_i32_e32 v157, 31, v156
	s_addc_u32 s9, s13, s9
	v_lshl_add_u64 v[180:181], v[156:157], 2, s[8:9]
	global_load_dwordx4 v[232:235], v[180:181], off offset:16
	global_load_dwordx4 v[236:239], v[180:181], off
	v_readlane_b32 s8, v253, 29
	v_readlane_b32 s9, v253, 30
	s_mov_b32 s1, 0x100000
	s_mov_b32 s66, s0
	s_mov_b32 s65, s4
	s_mov_b64 s[20:21], s[6:7]
	v_readlane_b32 s62, v255, 4
	v_readlane_b32 s63, v255, 5
	s_waitcnt vmcnt(0)
	v_ffbh_u32_e32 v132, v131
	v_min_u32_e32 v132, 32, v132
	v_lshlrev_b64 v[130:131], v132, v[130:131]
	v_min_u32_e32 v130, 1, v130
	v_or_b32_e32 v130, v131, v130
	v_cvt_f32_u32_e32 v130, v130
	v_sub_u32_e32 v131, 32, v132
	v_ldexp_f32 v130, v130, v131
	v_mul_f32_e32 v130, 0x37800000, v130
	v_fmamk_f32 v158, v130, 0x3a800000, v240
	v_mov_b32_e32 v130, v218
	v_mov_b32_e32 v131, v219
	v_cmp_gt_f32_e32 vcc, s53, v158
	v_mul_f32_e32 v164, 0x4b800000, v158
	v_ffbh_u32_e32 v132, v131
	v_min_u32_e32 v132, 32, v132
	v_lshlrev_b64 v[130:131], v132, v[130:131]
	v_min_u32_e32 v130, 1, v130
	v_or_b32_e32 v130, v131, v130
	v_cvt_f32_u32_e32 v130, v130
	v_sub_u32_e32 v131, 32, v132
	v_cndmask_b32_e32 v158, v158, v164, vcc
	v_rsq_f32_e32 v158, v158
	v_ldexp_f32 v130, v130, v131
	v_mul_f32_e32 v130, 0x37800000, v130
	v_fmamk_f32 v171, v130, 0x3a800000, v240
	v_mov_b32_e32 v130, v220
	v_mov_b32_e32 v131, v221
	v_mul_f32_e32 v164, 0x45800000, v158
	v_cndmask_b32_e32 v184, v158, v164, vcc
	v_cmp_gt_f32_e32 vcc, s53, v171
	v_mul_f32_e32 v158, 0x4b800000, v171
	v_ffbh_u32_e32 v132, v131
	v_min_u32_e32 v132, 32, v132
	v_lshlrev_b64 v[130:131], v132, v[130:131]
	v_min_u32_e32 v130, 1, v130
	v_or_b32_e32 v130, v131, v130
	v_cvt_f32_u32_e32 v130, v130
	v_sub_u32_e32 v131, 32, v132
	v_cndmask_b32_e32 v158, v171, v158, vcc
	v_rsq_f32_e32 v158, v158
	v_ldexp_f32 v130, v130, v131
	v_mul_f32_e32 v130, 0x37800000, v130
	v_fmamk_f32 v172, v130, 0x3a800000, v240
	v_mov_b32_e32 v130, v222
	v_mov_b32_e32 v131, v223
	v_mul_f32_e32 v164, 0x45800000, v158
	v_cndmask_b32_e32 v182, v158, v164, vcc
	v_cmp_gt_f32_e32 vcc, s53, v172
	v_mul_f32_e32 v158, 0x4b800000, v172
	v_ffbh_u32_e32 v132, v131
	v_min_u32_e32 v132, 32, v132
	v_lshlrev_b64 v[130:131], v132, v[130:131]
	v_min_u32_e32 v130, 1, v130
	v_or_b32_e32 v130, v131, v130
	v_cvt_f32_u32_e32 v130, v130
	v_sub_u32_e32 v131, 32, v132
	v_cndmask_b32_e32 v158, v172, v158, vcc
	v_rsq_f32_e32 v158, v158
	v_ldexp_f32 v130, v130, v131
	v_mul_f32_e32 v130, 0x37800000, v130
	v_fmamk_f32 v173, v130, 0x3a800000, v240
	v_mov_b32_e32 v130, v224
	v_mov_b32_e32 v131, v225
	v_mul_f32_e32 v164, 0x45800000, v158
	v_ffbh_u32_e32 v132, v131
	v_min_u32_e32 v132, 32, v132
	v_lshlrev_b64 v[130:131], v132, v[130:131]
	v_min_u32_e32 v130, 1, v130
	v_or_b32_e32 v130, v131, v130
	v_cvt_f32_u32_e32 v130, v130
	v_sub_u32_e32 v131, 32, v132
	v_ldexp_f32 v130, v130, v131
	v_mul_f32_e32 v130, 0x37800000, v130
	v_fmamk_f32 v174, v130, 0x3a800000, v240
	v_mov_b32_e32 v130, v226
	v_mov_b32_e32 v131, v227
	v_ffbh_u32_e32 v132, v131
	v_min_u32_e32 v132, 32, v132
	v_lshlrev_b64 v[130:131], v132, v[130:131]
	v_min_u32_e32 v130, 1, v130
	v_or_b32_e32 v130, v131, v130
	v_cvt_f32_u32_e32 v130, v130
	v_sub_u32_e32 v131, 32, v132
	v_ldexp_f32 v130, v130, v131
	v_mul_f32_e32 v130, 0x37800000, v130
	v_fmamk_f32 v175, v130, 0x3a800000, v240
	v_mov_b32_e32 v130, v228
	v_mov_b32_e32 v131, v229
	v_ffbh_u32_e32 v132, v131
	v_mov_b32_e32 v128, v230
	v_mov_b32_e32 v129, v231
	v_min_u32_e32 v132, 32, v132
	v_lshlrev_b64 v[130:131], v132, v[130:131]
	v_min_u32_e32 v130, 1, v130
	v_or_b32_e32 v130, v131, v130
	v_cvt_f32_u32_e32 v130, v130
	v_sub_u32_e32 v131, 32, v132
	v_ldexp_f32 v130, v130, v131
	v_mul_f32_e32 v130, 0x37800000, v130
	v_fmamk_f32 v177, v130, 0x3a800000, v240
	v_ffbh_u32_e32 v130, v129
	v_min_u32_e32 v130, 32, v130
	v_lshlrev_b64 v[128:129], v130, v[128:129]
	v_min_u32_e32 v128, 1, v128
	v_or_b32_e32 v128, v129, v128
	v_cvt_f32_u32_e32 v128, v128
	v_sub_u32_e32 v129, 32, v130
	v_ldexp_f32 v128, v128, v129
	v_mul_f32_e32 v128, 0x37800000, v128
	v_fmamk_f32 v179, v128, 0x3a800000, v240
	v_mov_b32_e32 v128, v232
	v_mov_b32_e32 v129, v233
	v_mov_b32_e32 v130, v234
	v_mov_b32_e32 v131, v235
	v_mov_b32_e32 v132, v236
	v_mov_b32_e32 v133, v237
	v_mov_b32_e32 v134, v238
	v_mov_b32_e32 v135, v239
	s_waitcnt vmcnt(0)
	v_pk_add_f32 v[148:149], v[130:131], 0 op_sel_hi:[1,0]
	v_pk_add_f32 v[152:153], v[134:135], 0 op_sel_hi:[1,0]
	v_pk_add_f32 v[154:155], v[132:133], 0 op_sel_hi:[1,0]
	v_pk_add_f32 v[150:151], v[128:129], 0 op_sel_hi:[1,0]
	global_load_dwordx4 v[128:131], v[180:181], off offset:528
	global_load_dwordx4 v[132:135], v[180:181], off offset:512
	v_cndmask_b32_e32 v180, v158, v164, vcc
	v_cmp_gt_f32_e32 vcc, s53, v173
	v_mul_f32_e32 v158, 0x4b800000, v173
	v_pk_fma_f32 v[122:123], v[122:123], v[184:185], v[148:149] op_sel_hi:[1,0,1]
	v_cndmask_b32_e32 v158, v173, v158, vcc
	v_rsq_f32_e32 v158, v158
	v_pk_fma_f32 v[126:127], v[126:127], v[184:185], v[152:153] op_sel_hi:[1,0,1]
	v_pk_fma_f32 v[124:125], v[124:125], v[184:185], v[154:155] op_sel_hi:[1,0,1]
	v_pk_fma_f32 v[120:121], v[120:121], v[184:185], v[150:151] op_sel_hi:[1,0,1]
	v_mul_f32_e32 v164, 0x45800000, v158
	v_cndmask_b32_e32 v178, v158, v164, vcc
	v_cmp_gt_f32_e32 vcc, s53, v174
	v_mul_f32_e32 v158, 0x4b800000, v174
	v_max_f32_e32 v122, 0, v122
	v_cndmask_b32_e32 v158, v174, v158, vcc
	v_rsq_f32_e32 v158, v158
	v_max_f32_e32 v124, 0, v124
	v_max_f32_e32 v120, 0, v120
	v_max_f32_e32 v121, 0, v121
	v_mul_f32_e32 v164, 0x45800000, v158
	v_cndmask_b32_e32 v176, v158, v164, vcc
	v_cmp_gt_f32_e32 vcc, s53, v175
	v_mul_f32_e32 v158, 0x4b800000, v175
	v_mul_f32_e32 v124, v124, v124
	v_cndmask_b32_e32 v158, v175, v158, vcc
	v_rsq_f32_e32 v158, v158
	v_mul_f32_e32 v120, v120, v120
	v_max_f32_e32 v125, 0, v125
	v_mul_f32_e32 v121, v121, v121
	v_mul_f32_e32 v164, 0x45800000, v158
	v_cndmask_b32_e32 v174, v158, v164, vcc
	v_cmp_gt_f32_e32 vcc, s53, v177
	v_mul_f32_e32 v158, 0x4b800000, v177
	v_max_f32_e32 v126, 0, v126
	v_cndmask_b32_e32 v158, v177, v158, vcc
	v_rsq_f32_e32 v158, v158
	v_mul_f32_e32 v125, v125, v125
	v_mul_f32_e32 v126, v126, v126
	v_pk_fma_f32 v[114:115], v[114:115], v[182:183], v[148:149] op_sel_hi:[1,0,1]
	v_mul_f32_e32 v164, 0x45800000, v158
	v_cndmask_b32_e32 v172, v158, v164, vcc
	v_cmp_gt_f32_e32 vcc, s53, v179
	v_mul_f32_e32 v158, 0x4b800000, v179
	v_pk_fma_f32 v[118:119], v[118:119], v[182:183], v[152:153] op_sel_hi:[1,0,1]
	v_cndmask_b32_e32 v158, v179, v158, vcc
	v_rsq_f32_e32 v158, v158
	v_pk_fma_f32 v[116:117], v[116:117], v[182:183], v[154:155] op_sel_hi:[1,0,1]
	v_pk_fma_f32 v[112:113], v[112:113], v[182:183], v[150:151] op_sel_hi:[1,0,1]
	v_max_f32_e32 v114, 0, v114
	v_mul_f32_e32 v164, 0x45800000, v158
	v_cndmask_b32_e32 v158, v158, v164, vcc
	v_mul_f32_e32 v164, v122, v122
	v_max_f32_e32 v122, 0, v127
	v_mul_f32_e32 v127, v122, v122
	v_max_f32_e32 v122, 0, v123
	v_mul_f32_e32 v165, v122, v122
	v_cvt_pk_bf16_f32 v122, v124, v125
	v_cvt_pk_bf16_f32 v123, v126, v127
	v_cvt_pk_bf16_f32 v124, v120, v121
	v_lshlrev_b64 v[120:121], 13, v[146:147]
	v_lshl_add_u64 v[120:121], s[8:9], 0, v[120:121]
	v_lshlrev_b64 v[126:127], 1, v[156:157]
	v_lshl_add_u64 v[120:121], v[120:121], 0, v[126:127]
	v_cvt_pk_bf16_f32 v125, v164, v165
	global_store_dwordx4 v[120:121], v[122:125], off
	v_max_f32_e32 v116, 0, v116
	v_max_f32_e32 v112, 0, v112
	v_mul_f32_e32 v122, v114, v114
	v_max_f32_e32 v114, 0, v119
	v_mul_f32_e32 v116, v116, v116
	v_mul_f32_e32 v112, v112, v112
	v_max_f32_e32 v117, 0, v117
	v_max_f32_e32 v113, 0, v113
	v_max_f32_e32 v118, 0, v118
	v_mul_f32_e32 v119, v114, v114
	v_max_f32_e32 v114, 0, v115
	v_mul_f32_e32 v117, v117, v117
	v_mul_f32_e32 v113, v113, v113
	v_mul_f32_e32 v118, v118, v118
	v_mul_f32_e32 v123, v114, v114
	v_cvt_pk_bf16_f32 v114, v116, v117
	v_cvt_pk_bf16_f32 v115, v118, v119
	v_cvt_pk_bf16_f32 v116, v112, v113
	v_or_b32_e32 v112, 16, v146
	v_ashrrev_i32_e32 v113, 31, v112
	v_lshlrev_b64 v[112:113], 13, v[112:113]
	v_lshl_add_u64 v[112:113], s[8:9], 0, v[112:113]
	v_pk_fma_f32 v[106:107], v[106:107], v[180:181], v[148:149] op_sel_hi:[1,0,1]
	v_lshl_add_u64 v[112:113], v[112:113], 0, v[126:127]
	v_pk_fma_f32 v[110:111], v[110:111], v[180:181], v[152:153] op_sel_hi:[1,0,1]
	v_pk_fma_f32 v[108:109], v[108:109], v[180:181], v[154:155] op_sel_hi:[1,0,1]
	v_pk_fma_f32 v[104:105], v[104:105], v[180:181], v[150:151] op_sel_hi:[1,0,1]
	v_max_f32_e32 v106, 0, v106
	v_cvt_pk_bf16_f32 v117, v122, v123
	global_store_dwordx4 v[112:113], v[114:117], off
	v_max_f32_e32 v108, 0, v108
	v_max_f32_e32 v104, 0, v104
	v_mul_f32_e32 v114, v106, v106
	v_max_f32_e32 v106, 0, v111
	v_mul_f32_e32 v108, v108, v108
	v_mul_f32_e32 v104, v104, v104
	v_max_f32_e32 v109, 0, v109
	v_max_f32_e32 v105, 0, v105
	v_max_f32_e32 v110, 0, v110
	v_mul_f32_e32 v111, v106, v106
	v_max_f32_e32 v106, 0, v107
	v_mul_f32_e32 v109, v109, v109
	v_mul_f32_e32 v105, v105, v105
	v_mul_f32_e32 v110, v110, v110
	v_mul_f32_e32 v115, v106, v106
	v_cvt_pk_bf16_f32 v106, v108, v109
	v_cvt_pk_bf16_f32 v107, v110, v111
	v_cvt_pk_bf16_f32 v108, v104, v105
	v_or_b32_e32 v104, 32, v146
	v_ashrrev_i32_e32 v105, 31, v104
	v_lshlrev_b64 v[104:105], 13, v[104:105]
	v_lshl_add_u64 v[104:105], s[8:9], 0, v[104:105]
	v_pk_fma_f32 v[98:99], v[98:99], v[178:179], v[148:149] op_sel_hi:[1,0,1]
	v_lshl_add_u64 v[104:105], v[104:105], 0, v[126:127]
	v_pk_fma_f32 v[102:103], v[102:103], v[178:179], v[152:153] op_sel_hi:[1,0,1]
	v_pk_fma_f32 v[100:101], v[100:101], v[178:179], v[154:155] op_sel_hi:[1,0,1]
	v_pk_fma_f32 v[96:97], v[96:97], v[178:179], v[150:151] op_sel_hi:[1,0,1]
	v_max_f32_e32 v98, 0, v98
	v_cvt_pk_bf16_f32 v109, v114, v115
	global_store_dwordx4 v[104:105], v[106:109], off
	v_max_f32_e32 v100, 0, v100
	v_max_f32_e32 v96, 0, v96
	v_mul_f32_e32 v106, v98, v98
	v_max_f32_e32 v98, 0, v103
	v_mul_f32_e32 v100, v100, v100
	v_mul_f32_e32 v96, v96, v96
	v_max_f32_e32 v101, 0, v101
	v_max_f32_e32 v97, 0, v97
	v_max_f32_e32 v102, 0, v102
	v_mul_f32_e32 v103, v98, v98
	v_max_f32_e32 v98, 0, v99
	v_mul_f32_e32 v101, v101, v101
	v_mul_f32_e32 v97, v97, v97
	v_mul_f32_e32 v102, v102, v102
	v_mul_f32_e32 v107, v98, v98
	v_cvt_pk_bf16_f32 v98, v100, v101
	v_cvt_pk_bf16_f32 v99, v102, v103
	v_cvt_pk_bf16_f32 v100, v96, v97
	v_or_b32_e32 v96, 48, v146
	v_ashrrev_i32_e32 v97, 31, v96
	v_lshlrev_b64 v[96:97], 13, v[96:97]
	v_lshl_add_u64 v[96:97], s[8:9], 0, v[96:97]
	v_pk_fma_f32 v[90:91], v[90:91], v[176:177], v[148:149] op_sel_hi:[1,0,1]
	v_lshl_add_u64 v[96:97], v[96:97], 0, v[126:127]
	v_pk_fma_f32 v[94:95], v[94:95], v[176:177], v[152:153] op_sel_hi:[1,0,1]
	v_max_f32_e32 v90, 0, v90
	v_cvt_pk_bf16_f32 v101, v106, v107
	global_store_dwordx4 v[96:97], v[98:101], off
	v_pk_fma_f32 v[92:93], v[92:93], v[176:177], v[154:155] op_sel_hi:[1,0,1]
	v_max_f32_e32 v94, 0, v94
	v_mul_f32_e32 v98, v90, v90
	v_max_f32_e32 v90, 0, v95
	v_max_f32_e32 v92, 0, v92
	v_max_f32_e32 v93, 0, v93
	v_mul_f32_e32 v94, v94, v94
	v_mul_f32_e32 v95, v90, v90
	v_max_f32_e32 v90, 0, v91
	v_pk_fma_f32 v[88:89], v[88:89], v[176:177], v[150:151] op_sel_hi:[1,0,1]
	v_mul_f32_e32 v92, v92, v92
	v_mul_f32_e32 v93, v93, v93
	v_mul_f32_e32 v99, v90, v90
	v_cvt_pk_bf16_f32 v90, v92, v93
	v_cvt_pk_bf16_f32 v91, v94, v95
	v_add_co_u32_e32 v94, vcc, s1, v120
	v_pk_fma_f32 v[82:83], v[82:83], v[174:175], v[148:149] op_sel_hi:[1,0,1]
	v_max_f32_e32 v88, 0, v88
	v_max_f32_e32 v89, 0, v89
	v_addc_co_u32_e32 v95, vcc, 0, v121, vcc
	v_pk_fma_f32 v[86:87], v[86:87], v[174:175], v[152:153] op_sel_hi:[1,0,1]
	v_max_f32_e32 v82, 0, v82
	v_mul_f32_e32 v88, v88, v88
	v_mul_f32_e32 v89, v89, v89
	v_cvt_pk_bf16_f32 v92, v88, v89
	v_cvt_pk_bf16_f32 v93, v98, v99
	global_store_dwordx4 v[94:95], v[90:93], off
	v_pk_fma_f32 v[84:85], v[84:85], v[174:175], v[154:155] op_sel_hi:[1,0,1]
	v_max_f32_e32 v86, 0, v86
	v_mul_f32_e32 v90, v82, v82
	v_max_f32_e32 v82, 0, v87
	v_max_f32_e32 v84, 0, v84
	v_max_f32_e32 v85, 0, v85
	v_mul_f32_e32 v86, v86, v86
	v_mul_f32_e32 v87, v82, v82
	v_max_f32_e32 v82, 0, v83
	s_mov_b32 s1, 0x120000
	v_pk_fma_f32 v[80:81], v[80:81], v[174:175], v[150:151] op_sel_hi:[1,0,1]
	v_mul_f32_e32 v84, v84, v84
	v_mul_f32_e32 v85, v85, v85
	v_mul_f32_e32 v91, v82, v82
	v_cvt_pk_bf16_f32 v82, v84, v85
	v_cvt_pk_bf16_f32 v83, v86, v87
	v_add_co_u32_e32 v86, vcc, s1, v120
	v_pk_fma_f32 v[74:75], v[74:75], v[172:173], v[148:149] op_sel_hi:[1,0,1]
	v_max_f32_e32 v80, 0, v80
	v_max_f32_e32 v81, 0, v81
	v_addc_co_u32_e32 v87, vcc, 0, v121, vcc
	v_pk_fma_f32 v[78:79], v[78:79], v[172:173], v[152:153] op_sel_hi:[1,0,1]
	v_max_f32_e32 v74, 0, v74
	v_mul_f32_e32 v80, v80, v80
	v_mul_f32_e32 v81, v81, v81
	v_cvt_pk_bf16_f32 v84, v80, v81
	v_cvt_pk_bf16_f32 v85, v90, v91
	global_store_dwordx4 v[86:87], v[82:85], off
	v_pk_fma_f32 v[76:77], v[76:77], v[172:173], v[154:155] op_sel_hi:[1,0,1]
	v_max_f32_e32 v78, 0, v78
	v_mul_f32_e32 v82, v74, v74
	v_max_f32_e32 v74, 0, v79
	v_max_f32_e32 v76, 0, v76
	v_max_f32_e32 v77, 0, v77
	v_mul_f32_e32 v78, v78, v78
	v_mul_f32_e32 v79, v74, v74
	v_max_f32_e32 v74, 0, v75
	s_mov_b32 s1, 0x140000
	v_pk_fma_f32 v[72:73], v[72:73], v[172:173], v[150:151] op_sel_hi:[1,0,1]
	v_mul_f32_e32 v76, v76, v76
	v_mul_f32_e32 v77, v77, v77
	v_mul_f32_e32 v83, v74, v74
	v_cvt_pk_bf16_f32 v74, v76, v77
	v_cvt_pk_bf16_f32 v75, v78, v79
	v_add_co_u32_e32 v78, vcc, s1, v120
	v_pk_fma_f32 v[58:59], v[58:59], v[158:159], v[148:149] op_sel_hi:[1,0,1]
	v_max_f32_e32 v72, 0, v72
	v_max_f32_e32 v73, 0, v73
	v_addc_co_u32_e32 v79, vcc, 0, v121, vcc
	v_pk_fma_f32 v[62:63], v[62:63], v[158:159], v[152:153] op_sel_hi:[1,0,1]
	v_max_f32_e32 v58, 0, v58
	v_mul_f32_e32 v72, v72, v72
	v_mul_f32_e32 v73, v73, v73
	v_cvt_pk_bf16_f32 v76, v72, v73
	v_cvt_pk_bf16_f32 v77, v82, v83
	global_store_dwordx4 v[78:79], v[74:77], off
	v_pk_fma_f32 v[60:61], v[60:61], v[158:159], v[154:155] op_sel_hi:[1,0,1]
	v_max_f32_e32 v62, 0, v62
	v_mul_f32_e32 v74, v58, v58
	v_max_f32_e32 v58, 0, v63
	v_max_f32_e32 v60, 0, v60
	v_max_f32_e32 v61, 0, v61
	v_mul_f32_e32 v62, v62, v62
	v_mul_f32_e32 v63, v58, v58
	v_max_f32_e32 v58, 0, v59
	s_mov_b32 s1, 0x160000
	v_pk_fma_f32 v[56:57], v[56:57], v[158:159], v[150:151] op_sel_hi:[1,0,1]
	v_mul_f32_e32 v60, v60, v60
	v_mul_f32_e32 v61, v61, v61
	v_mul_f32_e32 v75, v58, v58
	v_cvt_pk_bf16_f32 v58, v60, v61
	v_cvt_pk_bf16_f32 v59, v62, v63
	v_add_co_u32_e32 v62, vcc, s1, v120
	s_waitcnt vmcnt(7)
	v_pk_add_f32 v[134:135], v[134:135], 0 op_sel_hi:[1,0]
	v_max_f32_e32 v56, 0, v56
	v_max_f32_e32 v57, 0, v57
	v_addc_co_u32_e32 v63, vcc, 0, v121, vcc
	v_pk_add_f32 v[130:131], v[130:131], 0 op_sel_hi:[1,0]
	v_mul_f32_e32 v56, v56, v56
	v_mul_f32_e32 v57, v57, v57
	v_cvt_pk_bf16_f32 v60, v56, v57
	v_cvt_pk_bf16_f32 v61, v74, v75
	global_store_dwordx4 v[62:63], v[58:61], off
	v_pk_fma_f32 v[62:63], v[66:67], v[184:185], v[130:131] op_sel_hi:[1,0,1]
	v_pk_add_f32 v[132:133], v[132:133], 0 op_sel_hi:[1,0]
	v_pk_fma_f32 v[58:59], v[70:71], v[184:185], v[134:135] op_sel_hi:[1,0,1]
	v_pk_add_f32 v[128:129], v[128:129], 0 op_sel_hi:[1,0]
	v_max_f32_e32 v58, 0, v58
	v_mul_f32_e32 v66, v58, v58
	v_max_f32_e32 v58, 0, v62
	v_pk_fma_f32 v[60:61], v[68:69], v[184:185], v[132:133] op_sel_hi:[1,0,1]
	v_mul_f32_e32 v62, v58, v58
	v_max_f32_e32 v58, 0, v59
	v_pk_fma_f32 v[64:65], v[64:65], v[184:185], v[128:129] op_sel_hi:[1,0,1]
	v_max_f32_e32 v60, 0, v60
	v_max_f32_e32 v61, 0, v61
	v_mul_f32_e32 v59, v58, v58
	v_max_f32_e32 v58, 0, v63
	v_pk_fma_f32 v[48:49], v[48:49], v[182:183], v[128:129] op_sel_hi:[1,0,1]
	v_mul_f32_e32 v60, v60, v60
	v_max_f32_e32 v64, 0, v64
	v_mul_f32_e32 v61, v61, v61
	v_max_f32_e32 v65, 0, v65
	v_mul_f32_e32 v63, v58, v58
	v_cvt_pk_bf16_f32 v58, v60, v61
	v_pk_fma_f32 v[52:53], v[52:53], v[182:183], v[132:133] op_sel_hi:[1,0,1]
	v_pk_fma_f32 v[50:51], v[50:51], v[182:183], v[130:131] op_sel_hi:[1,0,1]
	v_max_f32_e32 v48, 0, v48
	v_mul_f32_e32 v64, v64, v64
	v_mul_f32_e32 v65, v65, v65
	v_cvt_pk_bf16_f32 v59, v66, v59
	v_cvt_pk_bf16_f32 v60, v64, v65
	v_cvt_pk_bf16_f32 v61, v62, v63
	global_store_dwordx4 v[120:121], v[58:61], off offset:256
	v_pk_fma_f32 v[54:55], v[54:55], v[182:183], v[134:135] op_sel_hi:[1,0,1]
	v_max_f32_e32 v49, 0, v49
	v_mul_f32_e32 v58, v48, v48
	v_max_f32_e32 v48, 0, v53
	v_max_f32_e32 v50, 0, v50
	v_max_f32_e32 v52, 0, v52
	v_mul_f32_e32 v48, v48, v48
	v_mul_f32_e32 v53, v49, v49
	v_max_f32_e32 v49, 0, v54
	v_mul_f32_e32 v54, v50, v50
	v_max_f32_e32 v50, 0, v55
	v_max_f32_e32 v51, 0, v51
	v_pk_fma_f32 v[40:41], v[40:41], v[180:181], v[128:129] op_sel_hi:[1,0,1]
	v_mul_f32_e32 v52, v52, v52
	v_mul_f32_e32 v49, v49, v49
	v_mul_f32_e32 v50, v50, v50
	v_mul_f32_e32 v51, v51, v51
	v_cvt_pk_bf16_f32 v48, v52, v48
	v_pk_fma_f32 v[44:45], v[44:45], v[180:181], v[132:133] op_sel_hi:[1,0,1]
	v_pk_fma_f32 v[42:43], v[42:43], v[180:181], v[130:131] op_sel_hi:[1,0,1]
	v_max_f32_e32 v40, 0, v40
	v_cvt_pk_bf16_f32 v49, v49, v50
	v_cvt_pk_bf16_f32 v50, v58, v53
	v_cvt_pk_bf16_f32 v51, v54, v51
	global_store_dwordx4 v[112:113], v[48:51], off offset:256
	v_pk_fma_f32 v[46:47], v[46:47], v[180:181], v[134:135] op_sel_hi:[1,0,1]
	v_max_f32_e32 v41, 0, v41
	v_mul_f32_e32 v48, v40, v40
	v_max_f32_e32 v40, 0, v45
	v_max_f32_e32 v42, 0, v42
	v_max_f32_e32 v44, 0, v44
	v_mul_f32_e32 v40, v40, v40
	v_mul_f32_e32 v45, v41, v41
	v_max_f32_e32 v41, 0, v46
	v_mul_f32_e32 v46, v42, v42
	v_max_f32_e32 v42, 0, v47
	v_max_f32_e32 v43, 0, v43
	v_pk_fma_f32 v[32:33], v[32:33], v[178:179], v[128:129] op_sel_hi:[1,0,1]
	v_mul_f32_e32 v44, v44, v44
	v_mul_f32_e32 v41, v41, v41
	v_mul_f32_e32 v42, v42, v42
	v_mul_f32_e32 v43, v43, v43
	v_cvt_pk_bf16_f32 v40, v44, v40
	v_pk_fma_f32 v[36:37], v[36:37], v[178:179], v[132:133] op_sel_hi:[1,0,1]
	v_pk_fma_f32 v[34:35], v[34:35], v[178:179], v[130:131] op_sel_hi:[1,0,1]
	v_max_f32_e32 v32, 0, v32
	v_cvt_pk_bf16_f32 v41, v41, v42
	v_cvt_pk_bf16_f32 v42, v48, v45
	v_cvt_pk_bf16_f32 v43, v46, v43
	global_store_dwordx4 v[104:105], v[40:43], off offset:256
	v_pk_fma_f32 v[38:39], v[38:39], v[178:179], v[134:135] op_sel_hi:[1,0,1]
	v_max_f32_e32 v33, 0, v33
	v_mul_f32_e32 v40, v32, v32
	v_max_f32_e32 v32, 0, v37
	v_max_f32_e32 v34, 0, v34
	v_max_f32_e32 v36, 0, v36
	v_mul_f32_e32 v32, v32, v32
	v_mul_f32_e32 v37, v33, v33
	v_max_f32_e32 v33, 0, v38
	v_mul_f32_e32 v38, v34, v34
	v_max_f32_e32 v34, 0, v39
	v_max_f32_e32 v35, 0, v35
	v_pk_fma_f32 v[24:25], v[24:25], v[176:177], v[128:129] op_sel_hi:[1,0,1]
	v_mul_f32_e32 v36, v36, v36
	v_mul_f32_e32 v33, v33, v33
	v_mul_f32_e32 v34, v34, v34
	v_mul_f32_e32 v35, v35, v35
	v_cvt_pk_bf16_f32 v32, v36, v32
	v_pk_fma_f32 v[28:29], v[28:29], v[176:177], v[132:133] op_sel_hi:[1,0,1]
	v_pk_fma_f32 v[26:27], v[26:27], v[176:177], v[130:131] op_sel_hi:[1,0,1]
	v_max_f32_e32 v24, 0, v24
	v_cvt_pk_bf16_f32 v33, v33, v34
	v_cvt_pk_bf16_f32 v34, v40, v37
	v_cvt_pk_bf16_f32 v35, v38, v35
	global_store_dwordx4 v[96:97], v[32:35], off offset:256
	v_pk_fma_f32 v[30:31], v[30:31], v[176:177], v[134:135] op_sel_hi:[1,0,1]
	v_max_f32_e32 v25, 0, v25
	v_mul_f32_e32 v32, v24, v24
	v_max_f32_e32 v24, 0, v29
	v_max_f32_e32 v26, 0, v26
	s_mov_b64 s[8:9], 0x100000
	v_max_f32_e32 v28, 0, v28
	v_mul_f32_e32 v24, v24, v24
	v_mul_f32_e32 v29, v25, v25
	v_max_f32_e32 v25, 0, v30
	v_mul_f32_e32 v30, v26, v26
	v_max_f32_e32 v26, 0, v31
	v_max_f32_e32 v27, 0, v27
	v_pk_fma_f32 v[16:17], v[16:17], v[174:175], v[128:129] op_sel_hi:[1,0,1]
	v_lshl_add_u64 v[88:89], v[120:121], 0, s[8:9]
	v_mul_f32_e32 v28, v28, v28
	v_mul_f32_e32 v25, v25, v25
	v_mul_f32_e32 v26, v26, v26
	v_mul_f32_e32 v27, v27, v27
	v_cvt_pk_bf16_f32 v24, v28, v24
	v_pk_fma_f32 v[20:21], v[20:21], v[174:175], v[132:133] op_sel_hi:[1,0,1]
	v_pk_fma_f32 v[18:19], v[18:19], v[174:175], v[130:131] op_sel_hi:[1,0,1]
	v_max_f32_e32 v16, 0, v16
	v_cvt_pk_bf16_f32 v25, v25, v26
	v_cvt_pk_bf16_f32 v26, v32, v29
	v_cvt_pk_bf16_f32 v27, v30, v27
	global_store_dwordx4 v[88:89], v[24:27], off offset:256
	v_pk_fma_f32 v[22:23], v[22:23], v[174:175], v[134:135] op_sel_hi:[1,0,1]
	v_max_f32_e32 v17, 0, v17
	v_mul_f32_e32 v24, v16, v16
	v_max_f32_e32 v16, 0, v21
	v_max_f32_e32 v18, 0, v18
	s_mov_b64 s[8:9], 0x120000
	v_max_f32_e32 v20, 0, v20
	v_mul_f32_e32 v16, v16, v16
	v_mul_f32_e32 v21, v17, v17
	v_max_f32_e32 v17, 0, v22
	v_mul_f32_e32 v22, v18, v18
	v_max_f32_e32 v18, 0, v23
	v_max_f32_e32 v19, 0, v19
	v_pk_fma_f32 v[8:9], v[8:9], v[172:173], v[128:129] op_sel_hi:[1,0,1]
	v_lshl_add_u64 v[80:81], v[120:121], 0, s[8:9]
	v_mul_f32_e32 v20, v20, v20
	v_mul_f32_e32 v17, v17, v17
	v_mul_f32_e32 v18, v18, v18
	v_mul_f32_e32 v19, v19, v19
	v_cvt_pk_bf16_f32 v16, v20, v16
	v_pk_fma_f32 v[12:13], v[12:13], v[172:173], v[132:133] op_sel_hi:[1,0,1]
	v_pk_fma_f32 v[10:11], v[10:11], v[172:173], v[130:131] op_sel_hi:[1,0,1]
	v_max_f32_e32 v8, 0, v8
	v_cvt_pk_bf16_f32 v17, v17, v18
	v_cvt_pk_bf16_f32 v18, v24, v21
	v_cvt_pk_bf16_f32 v19, v22, v19
	global_store_dwordx4 v[80:81], v[16:19], off offset:256
	v_pk_fma_f32 v[14:15], v[14:15], v[172:173], v[134:135] op_sel_hi:[1,0,1]
	v_max_f32_e32 v9, 0, v9
	v_mul_f32_e32 v16, v8, v8
	v_max_f32_e32 v8, 0, v13
	v_max_f32_e32 v10, 0, v10
	s_mov_b64 s[8:9], 0x140000
	v_max_f32_e32 v12, 0, v12
	v_mul_f32_e32 v8, v8, v8
	v_mul_f32_e32 v13, v9, v9
	v_max_f32_e32 v9, 0, v14
	v_mul_f32_e32 v14, v10, v10
	v_max_f32_e32 v10, 0, v15
	v_max_f32_e32 v11, 0, v11
	v_pk_fma_f32 v[2:3], v[2:3], v[158:159], v[130:131] op_sel_hi:[1,0,1]
	v_pk_fma_f32 v[0:1], v[0:1], v[158:159], v[128:129] op_sel_hi:[1,0,1]
	v_lshl_add_u64 v[72:73], v[120:121], 0, s[8:9]
	v_mul_f32_e32 v12, v12, v12
	v_mul_f32_e32 v9, v9, v9
	v_mul_f32_e32 v10, v10, v10
	v_mul_f32_e32 v11, v11, v11
	v_cvt_pk_bf16_f32 v8, v12, v8
	v_pk_fma_f32 v[6:7], v[6:7], v[158:159], v[134:135] op_sel_hi:[1,0,1]
	v_pk_fma_f32 v[4:5], v[4:5], v[158:159], v[132:133] op_sel_hi:[1,0,1]
	v_max_f32_e32 v0, 0, v0
	v_max_f32_e32 v1, 0, v1
	v_max_f32_e32 v2, 0, v2
	s_mov_b64 s[8:9], 0x160000
	v_cvt_pk_bf16_f32 v9, v9, v10
	v_cvt_pk_bf16_f32 v10, v16, v13
	v_cvt_pk_bf16_f32 v11, v14, v11
	global_store_dwordx4 v[72:73], v[8:11], off offset:256
	v_max_f32_e32 v3, 0, v3
	v_lshl_add_u64 v[56:57], v[120:121], 0, s[8:9]
	v_mul_f32_e32 v8, v0, v0
	v_max_f32_e32 v0, 0, v5
	v_mul_f32_e32 v5, v1, v1
	v_max_f32_e32 v1, 0, v6
	v_mul_f32_e32 v6, v2, v2
	v_max_f32_e32 v2, 0, v7
	v_max_f32_e32 v4, 0, v4
	v_mul_f32_e32 v0, v0, v0
	v_mul_f32_e32 v1, v1, v1
	v_mul_f32_e32 v2, v2, v2
	v_mul_f32_e32 v3, v3, v3
	s_and_b64 vcc, exec, s[2:3]
	s_mov_b64 s[8:9], s[58:59]
	v_mul_f32_e32 v4, v4, v4
	v_cvt_pk_bf16_f32 v0, v4, v0
	v_cvt_pk_bf16_f32 v1, v1, v2
	v_cvt_pk_bf16_f32 v2, v8, v5
	v_cvt_pk_bf16_f32 v3, v6, v3
	global_store_dwordx4 v[56:57], v[0:3], off offset:256
	s_cbranch_vccz .LBB0_343
	s_waitcnt vmcnt(0)
	s_mov_b32 s90, s62
	s_cmpk_gt_u32 s36, 0xff
	s_cbranch_scc1 .LBB0_354
	s_barrier
